# GEMM K-loops: counter/pointer adds after the last barrier moved into the last MFMA burst
# baseline (speedup 1.0000x reference)
.Lskw_P1:
	s_waitcnt lgkmcnt(0)
	s_barrier
	s_setprio 0
	s_waitcnt lgkmcnt(0)
	v_mfma_f32_16x16x32_bf16 v[124:127], v[148:151], v[186:189], v[124:127]
	v_mfma_f32_16x16x32_bf16 v[120:123], v[156:159], v[186:189], v[120:123]
	v_mfma_f32_16x16x32_bf16 v[108:111], v[148:151], v[194:197], v[108:111]
	v_mfma_f32_16x16x32_bf16 v[104:107], v[156:159], v[194:197], v[104:107]
	v_mfma_f32_16x16x32_bf16 v[92:95], v[148:151], v[202:205], v[92:95]
	v_mfma_f32_16x16x32_bf16 v[88:91], v[156:159], v[202:205], v[88:91]
	v_mfma_f32_16x16x32_bf16 v[76:79], v[148:151], v[210:213], v[76:79]
	v_mfma_f32_16x16x32_bf16 v[72:75], v[156:159], v[210:213], v[72:75]
	v_mfma_f32_16x16x32_bf16 v[124:127], v[152:155], v[190:193], v[124:127]
	v_mfma_f32_16x16x32_bf16 v[120:123], v[160:163], v[190:193], v[120:123]
	v_mfma_f32_16x16x32_bf16 v[108:111], v[152:155], v[198:201], v[108:111]
	v_mfma_f32_16x16x32_bf16 v[104:107], v[160:163], v[198:201], v[104:107]
	v_mfma_f32_16x16x32_bf16 v[92:95], v[152:155], v[206:209], v[92:95]
	v_mfma_f32_16x16x32_bf16 v[88:91], v[160:163], v[206:209], v[88:91]
	v_mfma_f32_16x16x32_bf16 v[76:79], v[152:155], v[214:217], v[76:79]
	v_mfma_f32_16x16x32_bf16 v[72:75], v[160:163], v[214:217], v[72:75]
	s_setprio 1
	s_setprio 0
	v_mfma_f32_16x16x32_bf16 v[116:119], v[164:167], v[186:189], v[116:119]
	v_mfma_f32_16x16x32_bf16 v[112:115], v[178:181], v[186:189], v[112:115]
	v_mfma_f32_16x16x32_bf16 v[100:103], v[164:167], v[194:197], v[100:103]
	v_mfma_f32_16x16x32_bf16 v[96:99], v[178:181], v[194:197], v[96:99]
	v_mfma_f32_16x16x32_bf16 v[84:87], v[164:167], v[202:205], v[84:87]
	v_mfma_f32_16x16x32_bf16 v[80:83], v[178:181], v[202:205], v[80:83]
	v_mfma_f32_16x16x32_bf16 v[68:71], v[164:167], v[210:213], v[68:71]
	v_mfma_f32_16x16x32_bf16 v[64:67], v[178:181], v[210:213], v[64:67]
	v_mfma_f32_16x16x32_bf16 v[116:119], v[168:171], v[190:193], v[116:119]
	v_mfma_f32_16x16x32_bf16 v[112:115], v[182:185], v[190:193], v[112:115]
	v_mfma_f32_16x16x32_bf16 v[100:103], v[168:171], v[198:201], v[100:103]
	v_mfma_f32_16x16x32_bf16 v[96:99], v[182:185], v[198:201], v[96:99]
	v_mfma_f32_16x16x32_bf16 v[84:87], v[168:171], v[206:209], v[84:87]
	v_mfma_f32_16x16x32_bf16 v[80:83], v[182:185], v[206:209], v[80:83]
	v_mfma_f32_16x16x32_bf16 v[68:71], v[168:171], v[214:217], v[68:71]
	v_mfma_f32_16x16x32_bf16 v[64:67], v[182:185], v[214:217], v[64:67]
	s_setprio 1
	s_barrier
	s_add_i32 s27, s64, s50
	v_lshl_add_u64 v[218:219], s[44:45], 0, v[130:131]
	s_mov_b32 m0, s27
	ds_read_b128 v[186:189], v177 offset:16384
	ds_read_b128 v[190:193], v177 offset:17408
	ds_read_b128 v[194:197], v177 offset:18432
	ds_read_b128 v[198:201], v177 offset:19456
	ds_read_b128 v[202:205], v177 offset:20480
	ds_read_b128 v[206:209], v177 offset:21504
	ds_read_b128 v[210:213], v177 offset:22528
	ds_read_b128 v[214:217], v177 offset:23552
	global_load_lds_dwordx4 v[218:219], off
	s_add_i32 m0, s27, 0x2000
	s_add_u32 s34, s44, 0x40000
	v_lshl_add_u64 v[220:221], s[44:45], 0, v[134:135]
	s_addc_u32 s35, s45, 0
	s_add_i32 s27, s65, s50
	global_load_lds_dwordx4 v[220:221], off
	v_lshl_add_u64 v[222:223], s[34:35], 0, v[130:131]
	s_mov_b32 m0, s27
	v_lshl_add_u64 v[224:225], s[46:47], 0, v[132:133]
	global_load_lds_dwordx4 v[222:223], off
	v_lshl_add_u64 v[222:223], s[34:35], 0, v[134:135]
	s_add_i32 m0, s27, 0x2000
	s_nop 0
	global_load_lds_dwordx4 v[222:223], off
	v_lshl_add_u64 v[222:223], s[46:47], 0, v[128:129]
	s_mov_b32 m0, s51
	s_nop 0
	global_load_lds_dwordx4 v[222:223], off
	s_mov_b32 m0, s52
	s_nop 0
	global_load_lds_dwordx4 v[224:225], off
	s_waitcnt vmcnt(8)
	s_waitcnt lgkmcnt(0)
	s_barrier
	s_setprio 0
	s_waitcnt lgkmcnt(0)
	v_mfma_f32_16x16x32_bf16 v[60:63], v[148:151], v[186:189], v[60:63]
	v_mfma_f32_16x16x32_bf16 v[56:59], v[156:159], v[186:189], v[56:59]
	v_mfma_f32_16x16x32_bf16 v[44:47], v[148:151], v[194:197], v[44:47]
	v_mfma_f32_16x16x32_bf16 v[40:43], v[156:159], v[194:197], v[40:43]
	v_mfma_f32_16x16x32_bf16 v[28:31], v[148:151], v[202:205], v[28:31]
	v_mfma_f32_16x16x32_bf16 v[24:27], v[156:159], v[202:205], v[24:27]
	v_mfma_f32_16x16x32_bf16 v[12:15], v[148:151], v[210:213], v[12:15]
	v_mfma_f32_16x16x32_bf16 v[8:11], v[156:159], v[210:213], v[8:11]
	v_mfma_f32_16x16x32_bf16 v[60:63], v[152:155], v[190:193], v[60:63]
	v_mfma_f32_16x16x32_bf16 v[56:59], v[160:163], v[190:193], v[56:59]
	v_mfma_f32_16x16x32_bf16 v[44:47], v[152:155], v[198:201], v[44:47]
	v_mfma_f32_16x16x32_bf16 v[40:43], v[160:163], v[198:201], v[40:43]
	v_mfma_f32_16x16x32_bf16 v[28:31], v[152:155], v[206:209], v[28:31]
	v_mfma_f32_16x16x32_bf16 v[24:27], v[160:163], v[206:209], v[24:27]
	v_mfma_f32_16x16x32_bf16 v[12:15], v[152:155], v[214:217], v[12:15]
	v_mfma_f32_16x16x32_bf16 v[8:11], v[160:163], v[214:217], v[8:11]
	s_setprio 1
	s_setprio 0
	v_mfma_f32_16x16x32_bf16 v[52:55], v[164:167], v[186:189], v[52:55]
	v_mfma_f32_16x16x32_bf16 v[48:51], v[178:181], v[186:189], v[48:51]
	v_mfma_f32_16x16x32_bf16 v[36:39], v[164:167], v[194:197], v[36:39]
	v_mfma_f32_16x16x32_bf16 v[32:35], v[178:181], v[194:197], v[32:35]
	v_mfma_f32_16x16x32_bf16 v[20:23], v[164:167], v[202:205], v[20:23]
	v_mfma_f32_16x16x32_bf16 v[16:19], v[178:181], v[202:205], v[16:19]
	v_mfma_f32_16x16x32_bf16 v[4:7], v[164:167], v[210:213], v[4:7]
	v_mfma_f32_16x16x32_bf16 v[0:3], v[178:181], v[210:213], v[0:3]
	v_mfma_f32_16x16x32_bf16 v[52:55], v[168:171], v[190:193], v[52:55]
	v_mfma_f32_16x16x32_bf16 v[48:51], v[182:185], v[190:193], v[48:51]
	v_mfma_f32_16x16x32_bf16 v[36:39], v[168:171], v[198:201], v[36:39]
	v_mfma_f32_16x16x32_bf16 v[32:35], v[182:185], v[198:201], v[32:35]
	v_mfma_f32_16x16x32_bf16 v[20:23], v[168:171], v[206:209], v[20:23]
	v_mfma_f32_16x16x32_bf16 v[16:19], v[182:185], v[206:209], v[16:19]
	v_mfma_f32_16x16x32_bf16 v[4:7], v[168:171], v[214:217], v[4:7]
	v_mfma_f32_16x16x32_bf16 v[0:3], v[182:185], v[214:217], v[0:3]
	s_setprio 1
	s_barrier
	s_add_i32 s27, 0, 0x18000
	v_add_u32_e32 v136, s27, v173
	s_add_i32 s30, 0, 0x1c000
	ds_read_b128 v[148:151], v136
	ds_read_b128 v[152:155], v136 offset:1024
	ds_read_b128 v[156:159], v136 offset:2048
	ds_read_b128 v[160:163], v136 offset:3072
	v_add_u32_e32 v136, s30, v173
	ds_read_b128 v[164:167], v136
	ds_read_b128 v[168:171], v136 offset:1024
	ds_read_b128 v[178:181], v136 offset:2048
	ds_read_b128 v[182:185], v136 offset:3072
	s_add_u32 s34, s46, 0x40000
	s_addc_u32 s35, s47, 0
	s_mov_b32 m0, s53
	v_lshl_add_u64 v[226:227], s[34:35], 0, v[128:129]
	ds_read_b128 v[186:189], v177 offset:32768
	ds_read_b128 v[190:193], v177 offset:33792
	ds_read_b128 v[194:197], v177 offset:34816
	ds_read_b128 v[198:201], v177 offset:35840
	ds_read_b128 v[202:205], v177 offset:36864
	ds_read_b128 v[206:209], v177 offset:37888
	ds_read_b128 v[210:213], v177 offset:38912
	ds_read_b128 v[214:217], v177 offset:39936
	global_load_lds_dwordx4 v[226:227], off
	v_lshl_add_u64 v[226:227], s[34:35], 0, v[132:133]
	s_mov_b32 m0, s54
	s_nop 0
	global_load_lds_dwordx4 v[226:227], off
	s_waitcnt vmcnt(8)
	s_waitcnt lgkmcnt(0)
	s_barrier
	s_setprio 0
	s_waitcnt lgkmcnt(0)
	v_mfma_f32_16x16x32_bf16 v[124:127], v[148:151], v[186:189], v[124:127]
	v_mfma_f32_16x16x32_bf16 v[120:123], v[156:159], v[186:189], v[120:123]
	v_mfma_f32_16x16x32_bf16 v[108:111], v[148:151], v[194:197], v[108:111]
	v_mfma_f32_16x16x32_bf16 v[104:107], v[156:159], v[194:197], v[104:107]
	v_mfma_f32_16x16x32_bf16 v[92:95], v[148:151], v[202:205], v[92:95]
	v_mfma_f32_16x16x32_bf16 v[88:91], v[156:159], v[202:205], v[88:91]
	v_mfma_f32_16x16x32_bf16 v[76:79], v[148:151], v[210:213], v[76:79]
	v_mfma_f32_16x16x32_bf16 v[72:75], v[156:159], v[210:213], v[72:75]
	v_mfma_f32_16x16x32_bf16 v[124:127], v[152:155], v[190:193], v[124:127]
	v_mfma_f32_16x16x32_bf16 v[120:123], v[160:163], v[190:193], v[120:123]
	v_mfma_f32_16x16x32_bf16 v[108:111], v[152:155], v[198:201], v[108:111]
	v_mfma_f32_16x16x32_bf16 v[104:107], v[160:163], v[198:201], v[104:107]
	v_mfma_f32_16x16x32_bf16 v[92:95], v[152:155], v[206:209], v[92:95]
	v_mfma_f32_16x16x32_bf16 v[88:91], v[160:163], v[206:209], v[88:91]
	v_mfma_f32_16x16x32_bf16 v[76:79], v[152:155], v[214:217], v[76:79]
	v_mfma_f32_16x16x32_bf16 v[72:75], v[160:163], v[214:217], v[72:75]
	s_setprio 1
	s_setprio 0
	v_mfma_f32_16x16x32_bf16 v[116:119], v[164:167], v[186:189], v[116:119]
	v_mfma_f32_16x16x32_bf16 v[112:115], v[178:181], v[186:189], v[112:115]
	v_mfma_f32_16x16x32_bf16 v[100:103], v[164:167], v[194:197], v[100:103]
	v_mfma_f32_16x16x32_bf16 v[96:99], v[178:181], v[194:197], v[96:99]
	v_mfma_f32_16x16x32_bf16 v[84:87], v[164:167], v[202:205], v[84:87]
	v_mfma_f32_16x16x32_bf16 v[80:83], v[178:181], v[202:205], v[80:83]
	v_mfma_f32_16x16x32_bf16 v[68:71], v[164:167], v[210:213], v[68:71]
	v_mfma_f32_16x16x32_bf16 v[64:67], v[178:181], v[210:213], v[64:67]
	v_mfma_f32_16x16x32_bf16 v[116:119], v[168:171], v[190:193], v[116:119]
	v_mfma_f32_16x16x32_bf16 v[112:115], v[182:185], v[190:193], v[112:115]
	v_mfma_f32_16x16x32_bf16 v[100:103], v[168:171], v[198:201], v[100:103]
	v_mfma_f32_16x16x32_bf16 v[96:99], v[182:185], v[198:201], v[96:99]
	v_mfma_f32_16x16x32_bf16 v[84:87], v[168:171], v[206:209], v[84:87]
	v_mfma_f32_16x16x32_bf16 v[80:83], v[182:185], v[206:209], v[80:83]
	v_mfma_f32_16x16x32_bf16 v[68:71], v[168:171], v[214:217], v[68:71]
	v_mfma_f32_16x16x32_bf16 v[64:67], v[182:185], v[214:217], v[64:67]
	s_setprio 1
	s_barrier
	s_add_i32 s27, s27, s50
	v_lshl_add_u64 v[218:219], v[218:219], 0, s[20:21]
	s_mov_b32 m0, s27
	ds_read_b128 v[186:189], v177 offset:49152
	ds_read_b128 v[190:193], v177 offset:50176
	ds_read_b128 v[194:197], v177 offset:51200
	ds_read_b128 v[198:201], v177 offset:52224
	ds_read_b128 v[202:205], v177 offset:53248
	ds_read_b128 v[206:209], v177 offset:54272
	ds_read_b128 v[210:213], v177 offset:55296
	ds_read_b128 v[214:217], v177 offset:56320
	global_load_lds_dwordx4 v[218:219], off
	s_add_i32 m0, s27, 0x2000
	s_add_u32 s34, s44, 0x40080
	v_lshl_add_u64 v[218:219], v[220:221], 0, s[20:21]
	s_addc_u32 s35, s45, 0
	s_add_i32 s27, s30, s50
	global_load_lds_dwordx4 v[218:219], off
	v_lshl_add_u64 v[218:219], s[34:35], 0, v[130:131]
	s_mov_b32 m0, s27
	s_nop 0
	global_load_lds_dwordx4 v[218:219], off
	v_lshl_add_u64 v[218:219], s[34:35], 0, v[134:135]
	s_add_i32 m0, s27, 0x2000
	s_nop 0
	global_load_lds_dwordx4 v[218:219], off
	v_lshl_add_u64 v[218:219], v[222:223], 0, s[20:21]
	s_mov_b32 m0, s62
	s_nop 0
	global_load_lds_dwordx4 v[218:219], off
	v_lshl_add_u64 v[218:219], v[224:225], 0, s[20:21]
	s_mov_b32 m0, s63
	s_nop 0
	global_load_lds_dwordx4 v[218:219], off
	s_waitcnt vmcnt(8)
	s_waitcnt lgkmcnt(0)
	s_barrier
	s_setprio 0
	s_waitcnt lgkmcnt(0)
	v_mfma_f32_16x16x32_bf16 v[60:63], v[148:151], v[186:189], v[60:63]
	v_mfma_f32_16x16x32_bf16 v[56:59], v[156:159], v[186:189], v[56:59]
	v_mfma_f32_16x16x32_bf16 v[44:47], v[148:151], v[194:197], v[44:47]
	v_mfma_f32_16x16x32_bf16 v[40:43], v[156:159], v[194:197], v[40:43]
	v_mfma_f32_16x16x32_bf16 v[28:31], v[148:151], v[202:205], v[28:31]
	v_mfma_f32_16x16x32_bf16 v[24:27], v[156:159], v[202:205], v[24:27]
	v_mfma_f32_16x16x32_bf16 v[12:15], v[148:151], v[210:213], v[12:15]
	v_mfma_f32_16x16x32_bf16 v[8:11], v[156:159], v[210:213], v[8:11]
	v_mfma_f32_16x16x32_bf16 v[60:63], v[152:155], v[190:193], v[60:63]
	s_add_i32 s25, s25, 2
	v_mfma_f32_16x16x32_bf16 v[56:59], v[160:163], v[190:193], v[56:59]
	s_add_u32 s42, s42, 0x100
	v_mfma_f32_16x16x32_bf16 v[44:47], v[152:155], v[198:201], v[44:47]
	s_addc_u32 s43, s43, 0
	v_mfma_f32_16x16x32_bf16 v[40:43], v[160:163], v[198:201], v[40:43]
	s_add_u32 s23, s23, 0x100
	v_mfma_f32_16x16x32_bf16 v[28:31], v[152:155], v[206:209], v[28:31]
	s_addc_u32 s24, s24, 0
	v_mfma_f32_16x16x32_bf16 v[24:27], v[160:163], v[206:209], v[24:27]
	v_mfma_f32_16x16x32_bf16 v[12:15], v[152:155], v[214:217], v[12:15]
	v_mfma_f32_16x16x32_bf16 v[8:11], v[160:163], v[214:217], v[8:11]
	s_setprio 1
	s_setprio 0
	v_mfma_f32_16x16x32_bf16 v[52:55], v[164:167], v[186:189], v[52:55]
	v_mfma_f32_16x16x32_bf16 v[48:51], v[178:181], v[186:189], v[48:51]
	v_mfma_f32_16x16x32_bf16 v[36:39], v[164:167], v[194:197], v[36:39]
	v_mfma_f32_16x16x32_bf16 v[32:35], v[178:181], v[194:197], v[32:35]
	v_mfma_f32_16x16x32_bf16 v[20:23], v[164:167], v[202:205], v[20:23]
	v_mfma_f32_16x16x32_bf16 v[16:19], v[178:181], v[202:205], v[16:19]
	v_mfma_f32_16x16x32_bf16 v[4:7], v[164:167], v[210:213], v[4:7]
	v_mfma_f32_16x16x32_bf16 v[0:3], v[178:181], v[210:213], v[0:3]
	v_mfma_f32_16x16x32_bf16 v[52:55], v[168:171], v[190:193], v[52:55]
	v_mfma_f32_16x16x32_bf16 v[48:51], v[182:185], v[190:193], v[48:51]
	v_mfma_f32_16x16x32_bf16 v[36:39], v[168:171], v[198:201], v[36:39]
	v_mfma_f32_16x16x32_bf16 v[32:35], v[182:185], v[198:201], v[32:35]
	v_mfma_f32_16x16x32_bf16 v[20:23], v[168:171], v[206:209], v[20:23]
	v_mfma_f32_16x16x32_bf16 v[16:19], v[182:185], v[206:209], v[16:19]
	v_mfma_f32_16x16x32_bf16 v[4:7], v[168:171], v[214:217], v[4:7]
	v_mfma_f32_16x16x32_bf16 v[0:3], v[182:185], v[214:217], v[0:3]
	s_setprio 1
	s_barrier
	s_cmp_gt_u32 s25, 13
	s_cbranch_scc0 .LBB5_248
	s_setprio 0
	s_nop 0
	s_nop 0
	s_nop 0
	s_nop 0
	s_nop 0
	s_nop 0
	s_nop 0
	s_nop 0
	s_nop 0
	s_nop 0
	s_nop 0
	s_nop 0
	s_nop 0
	s_and_b64 vcc, exec, s[18:19]
	s_cbranch_vccz .LBB5_251
	s_barrier

.Lskw_P3:
	s_waitcnt lgkmcnt(0)
	s_barrier
	s_setprio 0
	s_waitcnt lgkmcnt(0)
	v_mfma_f32_16x16x32_bf16 v[156:159], v[64:67], v[160:163], v[156:159]
	v_mfma_f32_16x16x32_bf16 v[152:155], v[72:75], v[160:163], v[152:155]
	v_mfma_f32_16x16x32_bf16 v[124:127], v[64:67], v[168:171], v[124:127]
	v_mfma_f32_16x16x32_bf16 v[120:123], v[72:75], v[168:171], v[120:123]
	v_mfma_f32_16x16x32_bf16 v[108:111], v[64:67], v[176:179], v[108:111]
	v_mfma_f32_16x16x32_bf16 v[104:107], v[72:75], v[176:179], v[104:107]
	v_mfma_f32_16x16x32_bf16 v[92:95], v[64:67], v[184:187], v[92:95]
	v_mfma_f32_16x16x32_bf16 v[88:91], v[72:75], v[184:187], v[88:91]
	v_mfma_f32_16x16x32_bf16 v[156:159], v[68:71], v[164:167], v[156:159]
	v_mfma_f32_16x16x32_bf16 v[152:155], v[76:79], v[164:167], v[152:155]
	v_mfma_f32_16x16x32_bf16 v[124:127], v[68:71], v[172:175], v[124:127]
	v_mfma_f32_16x16x32_bf16 v[120:123], v[76:79], v[172:175], v[120:123]
	v_mfma_f32_16x16x32_bf16 v[108:111], v[68:71], v[180:183], v[108:111]
	v_mfma_f32_16x16x32_bf16 v[104:107], v[76:79], v[180:183], v[104:107]
	v_mfma_f32_16x16x32_bf16 v[92:95], v[68:71], v[188:191], v[92:95]
	v_mfma_f32_16x16x32_bf16 v[88:91], v[76:79], v[188:191], v[88:91]
	s_setprio 1
	s_setprio 0
	v_mfma_f32_16x16x32_bf16 v[132:135], v[136:139], v[160:163], v[132:135]
	v_mfma_f32_16x16x32_bf16 v[128:131], v[144:147], v[160:163], v[128:131]
	v_mfma_f32_16x16x32_bf16 v[116:119], v[136:139], v[168:171], v[116:119]
	v_mfma_f32_16x16x32_bf16 v[112:115], v[144:147], v[168:171], v[112:115]
	v_mfma_f32_16x16x32_bf16 v[100:103], v[136:139], v[176:179], v[100:103]
	v_mfma_f32_16x16x32_bf16 v[96:99], v[144:147], v[176:179], v[96:99]
	v_mfma_f32_16x16x32_bf16 v[84:87], v[136:139], v[184:187], v[84:87]
	v_mfma_f32_16x16x32_bf16 v[80:83], v[144:147], v[184:187], v[80:83]
	v_mfma_f32_16x16x32_bf16 v[132:135], v[140:143], v[164:167], v[132:135]
	v_mfma_f32_16x16x32_bf16 v[128:131], v[148:151], v[164:167], v[128:131]
	v_mfma_f32_16x16x32_bf16 v[116:119], v[140:143], v[172:175], v[116:119]
	v_mfma_f32_16x16x32_bf16 v[112:115], v[148:151], v[172:175], v[112:115]
	v_mfma_f32_16x16x32_bf16 v[100:103], v[140:143], v[180:183], v[100:103]
	v_mfma_f32_16x16x32_bf16 v[96:99], v[148:151], v[180:183], v[96:99]
	v_mfma_f32_16x16x32_bf16 v[84:87], v[140:143], v[188:191], v[84:87]
	v_mfma_f32_16x16x32_bf16 v[80:83], v[148:151], v[188:191], v[80:83]
	s_setprio 1
	s_barrier
	s_add_i32 s35, s55, s46
	v_lshl_add_u64 v[192:193], s[42:43], 0, v[202:203]
	s_mov_b32 m0, s35
	ds_read_b128 v[160:163], v231 offset:16384
	ds_read_b128 v[164:167], v231 offset:17408
	ds_read_b128 v[168:171], v231 offset:18432
	ds_read_b128 v[172:175], v231 offset:19456
	ds_read_b128 v[176:179], v231 offset:20480
	ds_read_b128 v[180:183], v231 offset:21504
	ds_read_b128 v[184:187], v231 offset:22528
	ds_read_b128 v[188:191], v231 offset:23552
	global_load_lds_dwordx4 v[192:193], off
	s_add_i32 m0, s35, 0x2000
	s_add_u32 s58, s42, 0x40000
	v_lshl_add_u64 v[194:195], s[42:43], 0, v[206:207]
	s_addc_u32 s59, s43, 0
	s_add_i32 s35, s56, s46
	global_load_lds_dwordx4 v[194:195], off
	v_lshl_add_u64 v[196:197], s[58:59], 0, v[202:203]
	s_mov_b32 m0, s35
	v_lshl_add_u64 v[198:199], s[44:45], 0, v[204:205]
	global_load_lds_dwordx4 v[196:197], off
	v_lshl_add_u64 v[196:197], s[58:59], 0, v[206:207]
	s_add_i32 m0, s35, 0x2000
	s_nop 0
	global_load_lds_dwordx4 v[196:197], off
	v_lshl_add_u64 v[196:197], s[44:45], 0, v[200:201]
	s_mov_b32 m0, s39
	s_nop 0
	global_load_lds_dwordx4 v[196:197], off
	s_mov_b32 m0, s48
	s_nop 0
	global_load_lds_dwordx4 v[198:199], off
	s_waitcnt vmcnt(8)
	s_waitcnt lgkmcnt(0)
	s_barrier
	s_setprio 0
	s_waitcnt lgkmcnt(0)
	v_mfma_f32_16x16x32_bf16 v[60:63], v[64:67], v[160:163], v[60:63]
	v_mfma_f32_16x16x32_bf16 v[56:59], v[72:75], v[160:163], v[56:59]
	v_mfma_f32_16x16x32_bf16 v[44:47], v[64:67], v[168:171], v[44:47]
	v_mfma_f32_16x16x32_bf16 v[40:43], v[72:75], v[168:171], v[40:43]
	v_mfma_f32_16x16x32_bf16 v[28:31], v[64:67], v[176:179], v[28:31]
	v_mfma_f32_16x16x32_bf16 v[24:27], v[72:75], v[176:179], v[24:27]
	v_mfma_f32_16x16x32_bf16 v[12:15], v[64:67], v[184:187], v[12:15]
	v_mfma_f32_16x16x32_bf16 v[8:11], v[72:75], v[184:187], v[8:11]
	v_mfma_f32_16x16x32_bf16 v[60:63], v[68:71], v[164:167], v[60:63]
	v_mfma_f32_16x16x32_bf16 v[56:59], v[76:79], v[164:167], v[56:59]
	v_mfma_f32_16x16x32_bf16 v[44:47], v[68:71], v[172:175], v[44:47]
	v_mfma_f32_16x16x32_bf16 v[40:43], v[76:79], v[172:175], v[40:43]
	v_mfma_f32_16x16x32_bf16 v[28:31], v[68:71], v[180:183], v[28:31]
	v_mfma_f32_16x16x32_bf16 v[24:27], v[76:79], v[180:183], v[24:27]
	v_mfma_f32_16x16x32_bf16 v[12:15], v[68:71], v[188:191], v[12:15]
	v_mfma_f32_16x16x32_bf16 v[8:11], v[76:79], v[188:191], v[8:11]
	s_setprio 1
	s_setprio 0
	v_mfma_f32_16x16x32_bf16 v[52:55], v[136:139], v[160:163], v[52:55]
	v_mfma_f32_16x16x32_bf16 v[48:51], v[144:147], v[160:163], v[48:51]
	v_mfma_f32_16x16x32_bf16 v[36:39], v[136:139], v[168:171], v[36:39]
	v_mfma_f32_16x16x32_bf16 v[32:35], v[144:147], v[168:171], v[32:35]
	v_mfma_f32_16x16x32_bf16 v[20:23], v[136:139], v[176:179], v[20:23]
	v_mfma_f32_16x16x32_bf16 v[16:19], v[144:147], v[176:179], v[16:19]
	v_mfma_f32_16x16x32_bf16 v[4:7], v[136:139], v[184:187], v[4:7]
	v_mfma_f32_16x16x32_bf16 v[0:3], v[144:147], v[184:187], v[0:3]
	v_mfma_f32_16x16x32_bf16 v[52:55], v[140:143], v[164:167], v[52:55]
	v_mfma_f32_16x16x32_bf16 v[48:51], v[148:151], v[164:167], v[48:51]
	v_mfma_f32_16x16x32_bf16 v[36:39], v[140:143], v[172:175], v[36:39]
	v_mfma_f32_16x16x32_bf16 v[32:35], v[148:151], v[172:175], v[32:35]
	v_mfma_f32_16x16x32_bf16 v[20:23], v[140:143], v[180:183], v[20:23]
	v_mfma_f32_16x16x32_bf16 v[16:19], v[148:151], v[180:183], v[16:19]
	v_mfma_f32_16x16x32_bf16 v[4:7], v[140:143], v[188:191], v[4:7]
	v_mfma_f32_16x16x32_bf16 v[0:3], v[148:151], v[188:191], v[0:3]
	s_setprio 1
	s_barrier
	s_add_i32 s35, 0, 0x18000
	s_add_i32 s57, 0, 0x1c000
	v_add_u32_e32 v76, s35, v227
	v_add_u32_e32 v148, s57, v227
	ds_read_b128 v[64:67], v76
	ds_read_b128 v[68:71], v76 offset:1024
	ds_read_b128 v[72:75], v76 offset:2048
	ds_read_b128 v[76:79], v76 offset:3072
	ds_read_b128 v[136:139], v148
	ds_read_b128 v[140:143], v148 offset:1024
	ds_read_b128 v[144:147], v148 offset:2048
	ds_read_b128 v[148:151], v148 offset:3072
	s_add_u32 s44, s44, 0x40000
	s_addc_u32 s45, s45, 0
	s_mov_b32 m0, s49
	v_lshl_add_u64 v[216:217], s[44:45], 0, v[200:201]
	ds_read_b128 v[160:163], v231 offset:32768
	ds_read_b128 v[164:167], v231 offset:33792
	ds_read_b128 v[168:171], v231 offset:34816
	ds_read_b128 v[172:175], v231 offset:35840
	ds_read_b128 v[176:179], v231 offset:36864
	ds_read_b128 v[180:183], v231 offset:37888
	ds_read_b128 v[184:187], v231 offset:38912
	ds_read_b128 v[188:191], v231 offset:39936
	global_load_lds_dwordx4 v[216:217], off
	v_lshl_add_u64 v[216:217], s[44:45], 0, v[204:205]
	s_mov_b32 m0, s50
	s_nop 0
	global_load_lds_dwordx4 v[216:217], off
	s_waitcnt vmcnt(8)
	s_waitcnt lgkmcnt(0)
	s_barrier
	s_setprio 0
	s_waitcnt lgkmcnt(0)
	v_mfma_f32_16x16x32_bf16 v[156:159], v[64:67], v[160:163], v[156:159]
	v_mfma_f32_16x16x32_bf16 v[152:155], v[72:75], v[160:163], v[152:155]
	v_mfma_f32_16x16x32_bf16 v[124:127], v[64:67], v[168:171], v[124:127]
	v_mfma_f32_16x16x32_bf16 v[120:123], v[72:75], v[168:171], v[120:123]
	v_mfma_f32_16x16x32_bf16 v[108:111], v[64:67], v[176:179], v[108:111]
	v_mfma_f32_16x16x32_bf16 v[104:107], v[72:75], v[176:179], v[104:107]
	v_mfma_f32_16x16x32_bf16 v[92:95], v[64:67], v[184:187], v[92:95]
	v_mfma_f32_16x16x32_bf16 v[88:91], v[72:75], v[184:187], v[88:91]
	v_mfma_f32_16x16x32_bf16 v[156:159], v[68:71], v[164:167], v[156:159]
	v_mfma_f32_16x16x32_bf16 v[152:155], v[76:79], v[164:167], v[152:155]
	v_mfma_f32_16x16x32_bf16 v[124:127], v[68:71], v[172:175], v[124:127]
	v_mfma_f32_16x16x32_bf16 v[120:123], v[76:79], v[172:175], v[120:123]
	v_mfma_f32_16x16x32_bf16 v[108:111], v[68:71], v[180:183], v[108:111]
	v_mfma_f32_16x16x32_bf16 v[104:107], v[76:79], v[180:183], v[104:107]
	v_mfma_f32_16x16x32_bf16 v[92:95], v[68:71], v[188:191], v[92:95]
	v_mfma_f32_16x16x32_bf16 v[88:91], v[76:79], v[188:191], v[88:91]
	s_setprio 1
	s_setprio 0
	v_mfma_f32_16x16x32_bf16 v[132:135], v[136:139], v[160:163], v[132:135]
	v_mfma_f32_16x16x32_bf16 v[128:131], v[144:147], v[160:163], v[128:131]
	v_mfma_f32_16x16x32_bf16 v[116:119], v[136:139], v[168:171], v[116:119]
	v_mfma_f32_16x16x32_bf16 v[112:115], v[144:147], v[168:171], v[112:115]
	v_mfma_f32_16x16x32_bf16 v[100:103], v[136:139], v[176:179], v[100:103]
	v_mfma_f32_16x16x32_bf16 v[96:99], v[144:147], v[176:179], v[96:99]
	v_mfma_f32_16x16x32_bf16 v[84:87], v[136:139], v[184:187], v[84:87]
	v_mfma_f32_16x16x32_bf16 v[80:83], v[144:147], v[184:187], v[80:83]
	v_mfma_f32_16x16x32_bf16 v[132:135], v[140:143], v[164:167], v[132:135]
	v_mfma_f32_16x16x32_bf16 v[128:131], v[148:151], v[164:167], v[128:131]
	v_mfma_f32_16x16x32_bf16 v[116:119], v[140:143], v[172:175], v[116:119]
	v_mfma_f32_16x16x32_bf16 v[112:115], v[148:151], v[172:175], v[112:115]
	v_mfma_f32_16x16x32_bf16 v[100:103], v[140:143], v[180:183], v[100:103]
	v_mfma_f32_16x16x32_bf16 v[96:99], v[148:151], v[180:183], v[96:99]
	v_mfma_f32_16x16x32_bf16 v[84:87], v[140:143], v[188:191], v[84:87]
	v_mfma_f32_16x16x32_bf16 v[80:83], v[148:151], v[188:191], v[80:83]
	s_setprio 1
	s_barrier
	s_add_i32 s35, s35, s46
	v_lshl_add_u64 v[192:193], v[192:193], 0, s[16:17]
	s_mov_b32 m0, s35
	ds_read_b128 v[160:163], v231 offset:49152
	ds_read_b128 v[164:167], v231 offset:50176
	ds_read_b128 v[168:171], v231 offset:51200
	ds_read_b128 v[172:175], v231 offset:52224
	ds_read_b128 v[176:179], v231 offset:53248
	ds_read_b128 v[180:183], v231 offset:54272
	ds_read_b128 v[184:187], v231 offset:55296
	ds_read_b128 v[188:191], v231 offset:56320
	global_load_lds_dwordx4 v[192:193], off
	s_add_i32 m0, s35, 0x2000
	s_add_u32 s42, s42, 0x40080
	v_lshl_add_u64 v[192:193], v[194:195], 0, s[16:17]
	s_addc_u32 s43, s43, 0
	s_add_i32 s35, s57, s46
	global_load_lds_dwordx4 v[192:193], off
	v_lshl_add_u64 v[192:193], s[42:43], 0, v[202:203]
	s_mov_b32 m0, s35
	s_nop 0
	global_load_lds_dwordx4 v[192:193], off
	v_lshl_add_u64 v[192:193], s[42:43], 0, v[206:207]
	s_add_i32 m0, s35, 0x2000
	s_nop 0
	global_load_lds_dwordx4 v[192:193], off
	v_lshl_add_u64 v[192:193], v[196:197], 0, s[16:17]
	s_mov_b32 m0, s53
	s_nop 0
	global_load_lds_dwordx4 v[192:193], off
	v_lshl_add_u64 v[192:193], v[198:199], 0, s[16:17]
	s_mov_b32 m0, s54
	s_nop 0
	global_load_lds_dwordx4 v[192:193], off
	s_waitcnt vmcnt(8)
	s_waitcnt lgkmcnt(0)
	s_barrier
	s_setprio 0
	s_waitcnt lgkmcnt(0)
	v_mfma_f32_16x16x32_bf16 v[60:63], v[64:67], v[160:163], v[60:63]
	v_mfma_f32_16x16x32_bf16 v[56:59], v[72:75], v[160:163], v[56:59]
	v_mfma_f32_16x16x32_bf16 v[44:47], v[64:67], v[168:171], v[44:47]
	v_mfma_f32_16x16x32_bf16 v[40:43], v[72:75], v[168:171], v[40:43]
	v_mfma_f32_16x16x32_bf16 v[28:31], v[64:67], v[176:179], v[28:31]
	v_mfma_f32_16x16x32_bf16 v[24:27], v[72:75], v[176:179], v[24:27]
	v_mfma_f32_16x16x32_bf16 v[12:15], v[64:67], v[184:187], v[12:15]
	v_mfma_f32_16x16x32_bf16 v[8:11], v[72:75], v[184:187], v[8:11]
	v_mfma_f32_16x16x32_bf16 v[60:63], v[68:71], v[164:167], v[60:63]
	s_add_i32 s34, s34, 2
	v_mfma_f32_16x16x32_bf16 v[56:59], v[76:79], v[164:167], v[56:59]
	s_add_u32 s40, s40, 0x100
	v_mfma_f32_16x16x32_bf16 v[44:47], v[68:71], v[172:175], v[44:47]
	s_addc_u32 s41, s41, 0
	v_mfma_f32_16x16x32_bf16 v[40:43], v[76:79], v[172:175], v[40:43]
	s_add_u32 s30, s30, 0x100
	v_mfma_f32_16x16x32_bf16 v[28:31], v[68:71], v[180:183], v[28:31]
	s_addc_u32 s33, s33, 0
	v_mfma_f32_16x16x32_bf16 v[24:27], v[76:79], v[180:183], v[24:27]
	v_mfma_f32_16x16x32_bf16 v[12:15], v[68:71], v[188:191], v[12:15]
	v_mfma_f32_16x16x32_bf16 v[8:11], v[76:79], v[188:191], v[8:11]
	s_setprio 1
	s_setprio 0
	v_mfma_f32_16x16x32_bf16 v[52:55], v[136:139], v[160:163], v[52:55]
	v_mfma_f32_16x16x32_bf16 v[48:51], v[144:147], v[160:163], v[48:51]
	v_mfma_f32_16x16x32_bf16 v[36:39], v[136:139], v[168:171], v[36:39]
	v_mfma_f32_16x16x32_bf16 v[32:35], v[144:147], v[168:171], v[32:35]
	v_mfma_f32_16x16x32_bf16 v[20:23], v[136:139], v[176:179], v[20:23]
	v_mfma_f32_16x16x32_bf16 v[16:19], v[144:147], v[176:179], v[16:19]
	v_mfma_f32_16x16x32_bf16 v[4:7], v[136:139], v[184:187], v[4:7]
	v_mfma_f32_16x16x32_bf16 v[0:3], v[144:147], v[184:187], v[0:3]
	v_mfma_f32_16x16x32_bf16 v[52:55], v[140:143], v[164:167], v[52:55]
	v_mfma_f32_16x16x32_bf16 v[48:51], v[148:151], v[164:167], v[48:51]
	v_mfma_f32_16x16x32_bf16 v[36:39], v[140:143], v[172:175], v[36:39]
	v_mfma_f32_16x16x32_bf16 v[32:35], v[148:151], v[172:175], v[32:35]
	v_mfma_f32_16x16x32_bf16 v[20:23], v[140:143], v[180:183], v[20:23]
	v_mfma_f32_16x16x32_bf16 v[16:19], v[148:151], v[180:183], v[16:19]
	v_mfma_f32_16x16x32_bf16 v[4:7], v[140:143], v[188:191], v[4:7]
	v_mfma_f32_16x16x32_bf16 v[0:3], v[148:151], v[188:191], v[0:3]
	s_setprio 1
	s_barrier
	s_cmp_gt_u32 s34, 13
	s_cbranch_scc0 .LBB5_463
	s_setprio 0
	s_nop 0
	s_nop 0
	s_nop 0
	s_nop 0
	s_nop 0
	s_nop 0
	s_nop 0
	s_nop 0
	s_nop 0
	s_nop 0
	s_nop 0
	s_nop 0
	s_nop 0
	s_and_b64 vcc, exec, s[14:15]
	s_cbranch_vccz .LBB5_466
	s_barrier

.Lskw_P4:
	s_waitcnt lgkmcnt(0)
	s_barrier
	s_setprio 0
	s_waitcnt lgkmcnt(0)
	v_mfma_f32_16x16x32_bf16 v[124:127], v[128:131], v[160:163], v[124:127]
	v_mfma_f32_16x16x32_bf16 v[120:123], v[136:139], v[160:163], v[120:123]
	v_mfma_f32_16x16x32_bf16 v[108:111], v[128:131], v[168:171], v[108:111]
	v_mfma_f32_16x16x32_bf16 v[104:107], v[136:139], v[168:171], v[104:107]
	v_mfma_f32_16x16x32_bf16 v[92:95], v[128:131], v[192:195], v[92:95]
	v_mfma_f32_16x16x32_bf16 v[88:91], v[136:139], v[192:195], v[88:91]
	v_mfma_f32_16x16x32_bf16 v[76:79], v[128:131], v[200:203], v[76:79]
	v_mfma_f32_16x16x32_bf16 v[72:75], v[136:139], v[200:203], v[72:75]
	v_mfma_f32_16x16x32_bf16 v[124:127], v[132:135], v[164:167], v[124:127]
	v_mfma_f32_16x16x32_bf16 v[120:123], v[140:143], v[164:167], v[120:123]
	v_mfma_f32_16x16x32_bf16 v[108:111], v[132:135], v[172:175], v[108:111]
	v_mfma_f32_16x16x32_bf16 v[104:107], v[140:143], v[172:175], v[104:107]
	v_mfma_f32_16x16x32_bf16 v[92:95], v[132:135], v[196:199], v[92:95]
	v_mfma_f32_16x16x32_bf16 v[88:91], v[140:143], v[196:199], v[88:91]
	v_mfma_f32_16x16x32_bf16 v[76:79], v[132:135], v[212:215], v[76:79]
	v_mfma_f32_16x16x32_bf16 v[72:75], v[140:143], v[212:215], v[72:75]
	s_setprio 1
	s_setprio 0
	v_mfma_f32_16x16x32_bf16 v[116:119], v[144:147], v[160:163], v[116:119]
	v_mfma_f32_16x16x32_bf16 v[112:115], v[152:155], v[160:163], v[112:115]
	v_mfma_f32_16x16x32_bf16 v[100:103], v[144:147], v[168:171], v[100:103]
	v_mfma_f32_16x16x32_bf16 v[96:99], v[152:155], v[168:171], v[96:99]
	v_mfma_f32_16x16x32_bf16 v[84:87], v[144:147], v[192:195], v[84:87]
	v_mfma_f32_16x16x32_bf16 v[80:83], v[152:155], v[192:195], v[80:83]
	v_mfma_f32_16x16x32_bf16 v[68:71], v[144:147], v[200:203], v[68:71]
	v_mfma_f32_16x16x32_bf16 v[64:67], v[152:155], v[200:203], v[64:67]
	v_mfma_f32_16x16x32_bf16 v[116:119], v[148:151], v[164:167], v[116:119]
	v_mfma_f32_16x16x32_bf16 v[112:115], v[156:159], v[164:167], v[112:115]
	v_mfma_f32_16x16x32_bf16 v[100:103], v[148:151], v[172:175], v[100:103]
	v_mfma_f32_16x16x32_bf16 v[96:99], v[156:159], v[172:175], v[96:99]
	v_mfma_f32_16x16x32_bf16 v[84:87], v[148:151], v[196:199], v[84:87]
	v_mfma_f32_16x16x32_bf16 v[80:83], v[156:159], v[196:199], v[80:83]
	v_mfma_f32_16x16x32_bf16 v[68:71], v[148:151], v[212:215], v[68:71]
	v_mfma_f32_16x16x32_bf16 v[64:67], v[156:159], v[212:215], v[64:67]
	s_setprio 1
	s_barrier
	s_add_i32 s58, s51, s30
	v_lshl_add_u64 v[216:217], s[42:43], 0, v[178:179]
	s_mov_b32 m0, s58
	ds_read_b128 v[160:163], v211 offset:16384
	ds_read_b128 v[164:167], v211 offset:17408
	ds_read_b128 v[168:171], v211 offset:18432
	ds_read_b128 v[172:175], v211 offset:19456
	ds_read_b128 v[192:195], v211 offset:20480
	ds_read_b128 v[196:199], v211 offset:21504
	ds_read_b128 v[200:203], v211 offset:22528
	ds_read_b128 v[212:215], v211 offset:23552
	global_load_lds_dwordx4 v[216:217], off
	s_add_i32 m0, s58, 0x2000
	s_add_u32 s58, s42, 0x40000
	v_lshl_add_u64 v[218:219], s[42:43], 0, v[182:183]
	s_addc_u32 s59, s43, 0
	s_add_i32 s60, s52, s30
	global_load_lds_dwordx4 v[218:219], off
	v_lshl_add_u64 v[220:221], s[58:59], 0, v[178:179]
	s_mov_b32 m0, s60
	v_lshl_add_u64 v[222:223], s[44:45], 0, v[180:181]
	global_load_lds_dwordx4 v[220:221], off
	v_lshl_add_u64 v[220:221], s[58:59], 0, v[182:183]
	s_add_i32 m0, s60, 0x2000
	s_nop 0
	global_load_lds_dwordx4 v[220:221], off
	v_lshl_add_u64 v[220:221], s[44:45], 0, v[176:177]
	s_mov_b32 m0, s31
	s_nop 0
	global_load_lds_dwordx4 v[220:221], off
	s_mov_b32 m0, s33
	s_nop 0
	global_load_lds_dwordx4 v[222:223], off
	s_waitcnt vmcnt(8)
	s_waitcnt lgkmcnt(0)
	s_barrier
	s_setprio 0
	s_waitcnt lgkmcnt(0)
	v_mfma_f32_16x16x32_bf16 v[60:63], v[128:131], v[160:163], v[60:63]
	v_mfma_f32_16x16x32_bf16 v[56:59], v[136:139], v[160:163], v[56:59]
	v_mfma_f32_16x16x32_bf16 v[44:47], v[128:131], v[168:171], v[44:47]
	v_mfma_f32_16x16x32_bf16 v[40:43], v[136:139], v[168:171], v[40:43]
	v_mfma_f32_16x16x32_bf16 v[28:31], v[128:131], v[192:195], v[28:31]
	v_mfma_f32_16x16x32_bf16 v[24:27], v[136:139], v[192:195], v[24:27]
	v_mfma_f32_16x16x32_bf16 v[12:15], v[128:131], v[200:203], v[12:15]
	v_mfma_f32_16x16x32_bf16 v[8:11], v[136:139], v[200:203], v[8:11]
	v_mfma_f32_16x16x32_bf16 v[60:63], v[132:135], v[164:167], v[60:63]
	v_mfma_f32_16x16x32_bf16 v[56:59], v[140:143], v[164:167], v[56:59]
	v_mfma_f32_16x16x32_bf16 v[44:47], v[132:135], v[172:175], v[44:47]
	v_mfma_f32_16x16x32_bf16 v[40:43], v[140:143], v[172:175], v[40:43]
	v_mfma_f32_16x16x32_bf16 v[28:31], v[132:135], v[196:199], v[28:31]
	v_mfma_f32_16x16x32_bf16 v[24:27], v[140:143], v[196:199], v[24:27]
	v_mfma_f32_16x16x32_bf16 v[12:15], v[132:135], v[212:215], v[12:15]
	v_mfma_f32_16x16x32_bf16 v[8:11], v[140:143], v[212:215], v[8:11]
	s_setprio 1
	s_setprio 0
	v_mfma_f32_16x16x32_bf16 v[52:55], v[144:147], v[160:163], v[52:55]
	v_mfma_f32_16x16x32_bf16 v[48:51], v[152:155], v[160:163], v[48:51]
	v_mfma_f32_16x16x32_bf16 v[36:39], v[144:147], v[168:171], v[36:39]
	v_mfma_f32_16x16x32_bf16 v[32:35], v[152:155], v[168:171], v[32:35]
	v_mfma_f32_16x16x32_bf16 v[20:23], v[144:147], v[192:195], v[20:23]
	v_mfma_f32_16x16x32_bf16 v[16:19], v[152:155], v[192:195], v[16:19]
	v_mfma_f32_16x16x32_bf16 v[4:7], v[144:147], v[200:203], v[4:7]
	v_mfma_f32_16x16x32_bf16 v[0:3], v[152:155], v[200:203], v[0:3]
	v_mfma_f32_16x16x32_bf16 v[52:55], v[148:151], v[164:167], v[52:55]
	v_mfma_f32_16x16x32_bf16 v[48:51], v[156:159], v[164:167], v[48:51]
	v_mfma_f32_16x16x32_bf16 v[36:39], v[148:151], v[172:175], v[36:39]
	v_mfma_f32_16x16x32_bf16 v[32:35], v[156:159], v[172:175], v[32:35]
	v_mfma_f32_16x16x32_bf16 v[20:23], v[148:151], v[196:199], v[20:23]
	v_mfma_f32_16x16x32_bf16 v[16:19], v[156:159], v[196:199], v[16:19]
	v_mfma_f32_16x16x32_bf16 v[4:7], v[148:151], v[212:215], v[4:7]
	v_mfma_f32_16x16x32_bf16 v[0:3], v[156:159], v[212:215], v[0:3]
	s_setprio 1
	s_barrier
	s_add_i32 s58, 0, 0x18000
	s_add_i32 s59, 0, 0x1c000
	v_add_u32_e32 v140, s58, v205
	v_add_u32_e32 v156, s59, v205
	ds_read_b128 v[128:131], v140
	ds_read_b128 v[132:135], v140 offset:1024
	ds_read_b128 v[136:139], v140 offset:2048
	ds_read_b128 v[140:143], v140 offset:3072
	ds_read_b128 v[144:147], v156
	ds_read_b128 v[148:151], v156 offset:1024
	ds_read_b128 v[152:155], v156 offset:2048
	ds_read_b128 v[156:159], v156 offset:3072
	s_add_u32 s44, s44, 0x40000
	s_addc_u32 s45, s45, 0
	s_mov_b32 m0, s34
	v_lshl_add_u64 v[224:225], s[44:45], 0, v[176:177]
	ds_read_b128 v[160:163], v211 offset:32768
	ds_read_b128 v[164:167], v211 offset:33792
	ds_read_b128 v[168:171], v211 offset:34816
	ds_read_b128 v[172:175], v211 offset:35840
	ds_read_b128 v[192:195], v211 offset:36864
	ds_read_b128 v[196:199], v211 offset:37888
	ds_read_b128 v[200:203], v211 offset:38912
	ds_read_b128 v[212:215], v211 offset:39936
	global_load_lds_dwordx4 v[224:225], off
	v_lshl_add_u64 v[224:225], s[44:45], 0, v[180:181]
	s_mov_b32 m0, s35
	s_nop 0
	global_load_lds_dwordx4 v[224:225], off
	s_waitcnt vmcnt(8)
	s_waitcnt lgkmcnt(0)
	s_barrier
	s_setprio 0
	s_waitcnt lgkmcnt(0)
	v_mfma_f32_16x16x32_bf16 v[124:127], v[128:131], v[160:163], v[124:127]
	v_mfma_f32_16x16x32_bf16 v[120:123], v[136:139], v[160:163], v[120:123]
	v_mfma_f32_16x16x32_bf16 v[108:111], v[128:131], v[168:171], v[108:111]
	v_mfma_f32_16x16x32_bf16 v[104:107], v[136:139], v[168:171], v[104:107]
	v_mfma_f32_16x16x32_bf16 v[92:95], v[128:131], v[192:195], v[92:95]
	v_mfma_f32_16x16x32_bf16 v[88:91], v[136:139], v[192:195], v[88:91]
	v_mfma_f32_16x16x32_bf16 v[76:79], v[128:131], v[200:203], v[76:79]
	v_mfma_f32_16x16x32_bf16 v[72:75], v[136:139], v[200:203], v[72:75]
	v_mfma_f32_16x16x32_bf16 v[124:127], v[132:135], v[164:167], v[124:127]
	v_mfma_f32_16x16x32_bf16 v[120:123], v[140:143], v[164:167], v[120:123]
	v_mfma_f32_16x16x32_bf16 v[108:111], v[132:135], v[172:175], v[108:111]
	v_mfma_f32_16x16x32_bf16 v[104:107], v[140:143], v[172:175], v[104:107]
	v_mfma_f32_16x16x32_bf16 v[92:95], v[132:135], v[196:199], v[92:95]
	v_mfma_f32_16x16x32_bf16 v[88:91], v[140:143], v[196:199], v[88:91]
	v_mfma_f32_16x16x32_bf16 v[76:79], v[132:135], v[212:215], v[76:79]
	v_mfma_f32_16x16x32_bf16 v[72:75], v[140:143], v[212:215], v[72:75]
	s_setprio 1
	s_setprio 0
	v_mfma_f32_16x16x32_bf16 v[116:119], v[144:147], v[160:163], v[116:119]
	v_mfma_f32_16x16x32_bf16 v[112:115], v[152:155], v[160:163], v[112:115]
	v_mfma_f32_16x16x32_bf16 v[100:103], v[144:147], v[168:171], v[100:103]
	v_mfma_f32_16x16x32_bf16 v[96:99], v[152:155], v[168:171], v[96:99]
	v_mfma_f32_16x16x32_bf16 v[84:87], v[144:147], v[192:195], v[84:87]
	v_mfma_f32_16x16x32_bf16 v[80:83], v[152:155], v[192:195], v[80:83]
	v_mfma_f32_16x16x32_bf16 v[68:71], v[144:147], v[200:203], v[68:71]
	v_mfma_f32_16x16x32_bf16 v[64:67], v[152:155], v[200:203], v[64:67]
	v_mfma_f32_16x16x32_bf16 v[116:119], v[148:151], v[164:167], v[116:119]
	v_mfma_f32_16x16x32_bf16 v[112:115], v[156:159], v[164:167], v[112:115]
	v_mfma_f32_16x16x32_bf16 v[100:103], v[148:151], v[172:175], v[100:103]
	v_mfma_f32_16x16x32_bf16 v[96:99], v[156:159], v[172:175], v[96:99]
	v_mfma_f32_16x16x32_bf16 v[84:87], v[148:151], v[196:199], v[84:87]
	v_mfma_f32_16x16x32_bf16 v[80:83], v[156:159], v[196:199], v[80:83]
	v_mfma_f32_16x16x32_bf16 v[68:71], v[148:151], v[212:215], v[68:71]
	v_mfma_f32_16x16x32_bf16 v[64:67], v[156:159], v[212:215], v[64:67]
	s_setprio 1
	s_barrier
	s_add_i32 s44, s58, s30
	v_lshl_add_u64 v[216:217], v[216:217], 0, s[16:17]
	s_mov_b32 m0, s44
	ds_read_b128 v[160:163], v211 offset:49152
	ds_read_b128 v[164:167], v211 offset:50176
	ds_read_b128 v[168:171], v211 offset:51200
	ds_read_b128 v[172:175], v211 offset:52224
	ds_read_b128 v[192:195], v211 offset:53248
	ds_read_b128 v[196:199], v211 offset:54272
	ds_read_b128 v[200:203], v211 offset:55296
	ds_read_b128 v[212:215], v211 offset:56320
	global_load_lds_dwordx4 v[216:217], off
	s_add_i32 m0, s44, 0x2000
	s_add_u32 s42, s42, 0x40080
	v_lshl_add_u64 v[216:217], v[218:219], 0, s[16:17]
	s_addc_u32 s43, s43, 0
	s_add_i32 s44, s59, s30
	global_load_lds_dwordx4 v[216:217], off
	v_lshl_add_u64 v[216:217], s[42:43], 0, v[178:179]
	s_mov_b32 m0, s44
	s_nop 0
	global_load_lds_dwordx4 v[216:217], off
	v_lshl_add_u64 v[216:217], s[42:43], 0, v[182:183]
	s_add_i32 m0, s44, 0x2000
	s_nop 0
	global_load_lds_dwordx4 v[216:217], off
	v_lshl_add_u64 v[216:217], v[220:221], 0, s[16:17]
	s_mov_b32 m0, s49
	s_nop 0
	global_load_lds_dwordx4 v[216:217], off
	v_lshl_add_u64 v[216:217], v[222:223], 0, s[16:17]
	s_mov_b32 m0, s50
	s_nop 0
	global_load_lds_dwordx4 v[216:217], off
	s_waitcnt vmcnt(8)
	s_waitcnt lgkmcnt(0)
	s_barrier
	s_setprio 0
	s_waitcnt lgkmcnt(0)
	v_mfma_f32_16x16x32_bf16 v[60:63], v[128:131], v[160:163], v[60:63]
	v_mfma_f32_16x16x32_bf16 v[56:59], v[136:139], v[160:163], v[56:59]
	v_mfma_f32_16x16x32_bf16 v[44:47], v[128:131], v[168:171], v[44:47]
	v_mfma_f32_16x16x32_bf16 v[40:43], v[136:139], v[168:171], v[40:43]
	v_mfma_f32_16x16x32_bf16 v[28:31], v[128:131], v[192:195], v[28:31]
	v_mfma_f32_16x16x32_bf16 v[24:27], v[136:139], v[192:195], v[24:27]
	v_mfma_f32_16x16x32_bf16 v[12:15], v[128:131], v[200:203], v[12:15]
	v_mfma_f32_16x16x32_bf16 v[8:11], v[136:139], v[200:203], v[8:11]
	v_mfma_f32_16x16x32_bf16 v[60:63], v[132:135], v[164:167], v[60:63]
	s_add_i32 s57, s57, 2
	v_mfma_f32_16x16x32_bf16 v[56:59], v[140:143], v[164:167], v[56:59]
	s_add_u32 s40, s40, 0x100
	v_mfma_f32_16x16x32_bf16 v[44:47], v[132:135], v[172:175], v[44:47]
	s_addc_u32 s41, s41, 0
	v_mfma_f32_16x16x32_bf16 v[40:43], v[140:143], v[172:175], v[40:43]
	s_add_u32 s55, s55, 0x100
	v_mfma_f32_16x16x32_bf16 v[28:31], v[132:135], v[196:199], v[28:31]
	s_addc_u32 s56, s56, 0
	v_mfma_f32_16x16x32_bf16 v[24:27], v[140:143], v[196:199], v[24:27]
	v_mfma_f32_16x16x32_bf16 v[12:15], v[132:135], v[212:215], v[12:15]
	v_mfma_f32_16x16x32_bf16 v[8:11], v[140:143], v[212:215], v[8:11]
	s_setprio 1
	s_setprio 0
	v_mfma_f32_16x16x32_bf16 v[52:55], v[144:147], v[160:163], v[52:55]
	v_mfma_f32_16x16x32_bf16 v[48:51], v[152:155], v[160:163], v[48:51]
	v_mfma_f32_16x16x32_bf16 v[36:39], v[144:147], v[168:171], v[36:39]
	v_mfma_f32_16x16x32_bf16 v[32:35], v[152:155], v[168:171], v[32:35]
	v_mfma_f32_16x16x32_bf16 v[20:23], v[144:147], v[192:195], v[20:23]
	v_mfma_f32_16x16x32_bf16 v[16:19], v[152:155], v[192:195], v[16:19]
	v_mfma_f32_16x16x32_bf16 v[4:7], v[144:147], v[200:203], v[4:7]
	v_mfma_f32_16x16x32_bf16 v[0:3], v[152:155], v[200:203], v[0:3]
	v_mfma_f32_16x16x32_bf16 v[52:55], v[148:151], v[164:167], v[52:55]
	v_mfma_f32_16x16x32_bf16 v[48:51], v[156:159], v[164:167], v[48:51]
	v_mfma_f32_16x16x32_bf16 v[36:39], v[148:151], v[172:175], v[36:39]
	v_mfma_f32_16x16x32_bf16 v[32:35], v[156:159], v[172:175], v[32:35]
	v_mfma_f32_16x16x32_bf16 v[20:23], v[148:151], v[196:199], v[20:23]
	v_mfma_f32_16x16x32_bf16 v[16:19], v[156:159], v[196:199], v[16:19]
	v_mfma_f32_16x16x32_bf16 v[4:7], v[148:151], v[212:215], v[4:7]
	v_mfma_f32_16x16x32_bf16 v[0:3], v[156:159], v[212:215], v[0:3]
	s_setprio 1
	s_barrier
	s_cmp_gt_u32 s57, 13
	s_cbranch_scc0 .LBB5_536
	s_setprio 0
	s_nop 0
	s_nop 0
	s_nop 0
	s_nop 0
	s_nop 0
	s_nop 0
	s_nop 0
	s_nop 0
	s_nop 0
	s_nop 0
	s_nop 0
	s_nop 0
	s_nop 0
	s_and_b64 vcc, exec, s[14:15]
	s_cbranch_vccz .LBB5_539
	s_barrier

.Lskw_P5:
	s_waitcnt lgkmcnt(0)
	s_barrier
	s_setprio 0
	s_waitcnt lgkmcnt(0)
	v_mfma_f32_16x16x32_bf16 v[140:143], v[32:35], v[192:195], v[140:143]
	v_mfma_f32_16x16x32_bf16 v[136:139], v[40:43], v[192:195], v[136:139]
	v_mfma_f32_16x16x32_bf16 v[124:127], v[32:35], v[200:203], v[124:127]
	v_mfma_f32_16x16x32_bf16 v[120:123], v[40:43], v[200:203], v[120:123]
	v_mfma_f32_16x16x32_bf16 v[108:111], v[32:35], v[208:211], v[108:111]
	v_mfma_f32_16x16x32_bf16 v[104:107], v[40:43], v[208:211], v[104:107]
	v_mfma_f32_16x16x32_bf16 v[92:95], v[32:35], v[216:219], v[92:95]
	v_mfma_f32_16x16x32_bf16 v[88:91], v[40:43], v[216:219], v[88:91]
	v_mfma_f32_16x16x32_bf16 v[140:143], v[36:39], v[196:199], v[140:143]
	v_mfma_f32_16x16x32_bf16 v[136:139], v[44:47], v[196:199], v[136:139]
	v_mfma_f32_16x16x32_bf16 v[124:127], v[36:39], v[204:207], v[124:127]
	v_mfma_f32_16x16x32_bf16 v[120:123], v[44:47], v[204:207], v[120:123]
	v_mfma_f32_16x16x32_bf16 v[108:111], v[36:39], v[212:215], v[108:111]
	v_mfma_f32_16x16x32_bf16 v[104:107], v[44:47], v[212:215], v[104:107]
	v_mfma_f32_16x16x32_bf16 v[92:95], v[36:39], v[220:223], v[92:95]
	v_mfma_f32_16x16x32_bf16 v[88:91], v[44:47], v[220:223], v[88:91]
	s_setprio 1
	s_setprio 0
	v_mfma_f32_16x16x32_bf16 v[132:135], v[144:147], v[192:195], v[132:135]
	v_mfma_f32_16x16x32_bf16 v[128:131], v[152:155], v[192:195], v[128:131]
	v_mfma_f32_16x16x32_bf16 v[116:119], v[144:147], v[200:203], v[116:119]
	v_mfma_f32_16x16x32_bf16 v[112:115], v[152:155], v[200:203], v[112:115]
	v_mfma_f32_16x16x32_bf16 v[100:103], v[144:147], v[208:211], v[100:103]
	v_mfma_f32_16x16x32_bf16 v[96:99], v[152:155], v[208:211], v[96:99]
	v_mfma_f32_16x16x32_bf16 v[84:87], v[144:147], v[216:219], v[84:87]
	v_mfma_f32_16x16x32_bf16 v[80:83], v[152:155], v[216:219], v[80:83]
	v_mfma_f32_16x16x32_bf16 v[132:135], v[148:151], v[196:199], v[132:135]
	v_mfma_f32_16x16x32_bf16 v[128:131], v[156:159], v[196:199], v[128:131]
	v_mfma_f32_16x16x32_bf16 v[116:119], v[148:151], v[204:207], v[116:119]
	v_mfma_f32_16x16x32_bf16 v[112:115], v[156:159], v[204:207], v[112:115]
	v_mfma_f32_16x16x32_bf16 v[100:103], v[148:151], v[212:215], v[100:103]
	v_mfma_f32_16x16x32_bf16 v[96:99], v[156:159], v[212:215], v[96:99]
	v_mfma_f32_16x16x32_bf16 v[84:87], v[148:151], v[220:223], v[84:87]
	v_mfma_f32_16x16x32_bf16 v[80:83], v[156:159], v[220:223], v[80:83]
	s_setprio 1
	s_barrier
	s_add_i32 s34, s80, s60
	v_lshl_add_u64 v[180:181], s[8:9], 0, v[162:163]
	s_mov_b32 m0, s34
	ds_read_b128 v[192:195], v188 offset:16384
	ds_read_b128 v[196:199], v188 offset:17408
	ds_read_b128 v[200:203], v188 offset:18432
	ds_read_b128 v[204:207], v188 offset:19456
	ds_read_b128 v[208:211], v188 offset:20480
	ds_read_b128 v[212:215], v188 offset:21504
	ds_read_b128 v[216:219], v188 offset:22528
	ds_read_b128 v[220:223], v188 offset:23552
	global_load_lds_dwordx4 v[180:181], off
	s_add_i32 m0, s34, 0x2000
	s_add_u32 s34, s8, 0x40000
	v_lshl_add_u64 v[224:225], s[8:9], 0, v[166:167]
	s_addc_u32 s35, s9, 0
	s_add_i32 s49, s81, s60
	global_load_lds_dwordx4 v[224:225], off
	v_lshl_add_u64 v[226:227], s[34:35], 0, v[162:163]
	s_mov_b32 m0, s49
	v_lshl_add_u64 v[228:229], s[56:57], 0, v[164:165]
	global_load_lds_dwordx4 v[226:227], off
	v_lshl_add_u64 v[226:227], s[34:35], 0, v[166:167]
	s_add_i32 m0, s49, 0x2000
	s_nop 0
	global_load_lds_dwordx4 v[226:227], off
	v_lshl_add_u64 v[226:227], s[56:57], 0, v[160:161]
	s_mov_b32 m0, s61
	s_nop 0
	global_load_lds_dwordx4 v[226:227], off
	s_mov_b32 m0, s62
	s_nop 0
	global_load_lds_dwordx4 v[228:229], off
	s_waitcnt vmcnt(8)
	s_waitcnt lgkmcnt(0)
	s_barrier
	s_setprio 0
	s_waitcnt lgkmcnt(0)
	v_mfma_f32_16x16x32_bf16 v[76:79], v[32:35], v[192:195], v[76:79]
	v_mfma_f32_16x16x32_bf16 v[72:75], v[40:43], v[192:195], v[72:75]
	v_mfma_f32_16x16x32_bf16 v[60:63], v[32:35], v[200:203], v[60:63]
	v_mfma_f32_16x16x32_bf16 v[56:59], v[40:43], v[200:203], v[56:59]
	v_mfma_f32_16x16x32_bf16 v[28:31], v[32:35], v[208:211], v[28:31]
	v_mfma_f32_16x16x32_bf16 v[24:27], v[40:43], v[208:211], v[24:27]
	v_mfma_f32_16x16x32_bf16 v[12:15], v[32:35], v[216:219], v[12:15]
	v_mfma_f32_16x16x32_bf16 v[8:11], v[40:43], v[216:219], v[8:11]
	v_mfma_f32_16x16x32_bf16 v[76:79], v[36:39], v[196:199], v[76:79]
	v_mfma_f32_16x16x32_bf16 v[72:75], v[44:47], v[196:199], v[72:75]
	v_mfma_f32_16x16x32_bf16 v[60:63], v[36:39], v[204:207], v[60:63]
	v_mfma_f32_16x16x32_bf16 v[56:59], v[44:47], v[204:207], v[56:59]
	v_mfma_f32_16x16x32_bf16 v[28:31], v[36:39], v[212:215], v[28:31]
	v_mfma_f32_16x16x32_bf16 v[24:27], v[44:47], v[212:215], v[24:27]
	v_mfma_f32_16x16x32_bf16 v[12:15], v[36:39], v[220:223], v[12:15]
	v_mfma_f32_16x16x32_bf16 v[8:11], v[44:47], v[220:223], v[8:11]
	s_setprio 1
	s_setprio 0
	v_mfma_f32_16x16x32_bf16 v[20:23], v[144:147], v[208:211], v[20:23]
	v_mfma_f32_16x16x32_bf16 v[16:19], v[152:155], v[208:211], v[16:19]
	v_mfma_f32_16x16x32_bf16 v[4:7], v[144:147], v[216:219], v[4:7]
	v_mfma_f32_16x16x32_bf16 v[0:3], v[152:155], v[216:219], v[0:3]
	v_mfma_f32_16x16x32_bf16 v[32:35], v[144:147], v[192:195], v[68:71]
	v_mfma_f32_16x16x32_bf16 v[36:39], v[152:155], v[192:195], v[64:67]
	v_mfma_f32_16x16x32_bf16 v[40:43], v[144:147], v[200:203], v[52:55]
	v_mfma_f32_16x16x32_bf16 v[44:47], v[152:155], v[200:203], v[48:51]
	v_mfma_f32_16x16x32_bf16 v[20:23], v[148:151], v[212:215], v[20:23]
	v_mfma_f32_16x16x32_bf16 v[16:19], v[156:159], v[212:215], v[16:19]
	v_mfma_f32_16x16x32_bf16 v[4:7], v[148:151], v[220:223], v[4:7]
	v_mfma_f32_16x16x32_bf16 v[0:3], v[156:159], v[220:223], v[0:3]
	v_mfma_f32_16x16x32_bf16 v[32:35], v[148:151], v[196:199], v[32:35]
	v_mfma_f32_16x16x32_bf16 v[36:39], v[156:159], v[196:199], v[36:39]
	v_mfma_f32_16x16x32_bf16 v[40:43], v[148:151], v[204:207], v[40:43]
	v_mfma_f32_16x16x32_bf16 v[44:47], v[156:159], v[204:207], v[44:47]
	s_setprio 1
	s_barrier
	s_add_i32 s49, 0, 0x18000
	s_add_i32 s51, 0, 0x1c000
	v_add_u32_e32 v68, s49, v183
	v_add_u32_e32 v156, s51, v183
	ds_read_b128 v[48:51], v68
	ds_read_b128 v[52:55], v68 offset:1024
	ds_read_b128 v[64:67], v68 offset:2048
	ds_read_b128 v[68:71], v68 offset:3072
	ds_read_b128 v[144:147], v156
	ds_read_b128 v[148:151], v156 offset:1024
	ds_read_b128 v[152:155], v156 offset:2048
	ds_read_b128 v[156:159], v156 offset:3072
	s_add_u32 s34, s56, 0x40000
	s_addc_u32 s35, s57, 0
	s_mov_b32 m0, s63
	v_lshl_add_u64 v[230:231], s[34:35], 0, v[160:161]
	ds_read_b128 v[192:195], v188 offset:32768
	ds_read_b128 v[196:199], v188 offset:33792
	ds_read_b128 v[200:203], v188 offset:34816
	ds_read_b128 v[204:207], v188 offset:35840
	ds_read_b128 v[208:211], v188 offset:36864
	ds_read_b128 v[212:215], v188 offset:37888
	ds_read_b128 v[216:219], v188 offset:38912
	ds_read_b128 v[220:223], v188 offset:39936
	global_load_lds_dwordx4 v[230:231], off
	v_lshl_add_u64 v[230:231], s[34:35], 0, v[164:165]
	s_mov_b32 m0, s64
	s_nop 0
	global_load_lds_dwordx4 v[230:231], off
	s_waitcnt vmcnt(8)
	s_waitcnt lgkmcnt(0)
	s_barrier
	s_setprio 0
	s_waitcnt lgkmcnt(0)
	v_mfma_f32_16x16x32_bf16 v[140:143], v[48:51], v[192:195], v[140:143]
	v_mfma_f32_16x16x32_bf16 v[136:139], v[64:67], v[192:195], v[136:139]
	v_mfma_f32_16x16x32_bf16 v[124:127], v[48:51], v[200:203], v[124:127]
	v_mfma_f32_16x16x32_bf16 v[120:123], v[64:67], v[200:203], v[120:123]
	v_mfma_f32_16x16x32_bf16 v[108:111], v[48:51], v[208:211], v[108:111]
	v_mfma_f32_16x16x32_bf16 v[104:107], v[64:67], v[208:211], v[104:107]
	v_mfma_f32_16x16x32_bf16 v[92:95], v[48:51], v[216:219], v[92:95]
	v_mfma_f32_16x16x32_bf16 v[88:91], v[64:67], v[216:219], v[88:91]
	v_mfma_f32_16x16x32_bf16 v[140:143], v[52:55], v[196:199], v[140:143]
	v_mfma_f32_16x16x32_bf16 v[136:139], v[68:71], v[196:199], v[136:139]
	v_mfma_f32_16x16x32_bf16 v[124:127], v[52:55], v[204:207], v[124:127]
	v_mfma_f32_16x16x32_bf16 v[120:123], v[68:71], v[204:207], v[120:123]
	v_mfma_f32_16x16x32_bf16 v[108:111], v[52:55], v[212:215], v[108:111]
	v_mfma_f32_16x16x32_bf16 v[104:107], v[68:71], v[212:215], v[104:107]
	v_mfma_f32_16x16x32_bf16 v[92:95], v[52:55], v[220:223], v[92:95]
	v_mfma_f32_16x16x32_bf16 v[88:91], v[68:71], v[220:223], v[88:91]
	s_setprio 1
	s_setprio 0
	v_mfma_f32_16x16x32_bf16 v[132:135], v[144:147], v[192:195], v[132:135]
	v_mfma_f32_16x16x32_bf16 v[128:131], v[152:155], v[192:195], v[128:131]
	v_mfma_f32_16x16x32_bf16 v[116:119], v[144:147], v[200:203], v[116:119]
	v_mfma_f32_16x16x32_bf16 v[112:115], v[152:155], v[200:203], v[112:115]
	v_mfma_f32_16x16x32_bf16 v[100:103], v[144:147], v[208:211], v[100:103]
	v_mfma_f32_16x16x32_bf16 v[96:99], v[152:155], v[208:211], v[96:99]
	v_mfma_f32_16x16x32_bf16 v[84:87], v[144:147], v[216:219], v[84:87]
	v_mfma_f32_16x16x32_bf16 v[80:83], v[152:155], v[216:219], v[80:83]
	v_mfma_f32_16x16x32_bf16 v[132:135], v[148:151], v[196:199], v[132:135]
	v_mfma_f32_16x16x32_bf16 v[128:131], v[156:159], v[196:199], v[128:131]
	v_mfma_f32_16x16x32_bf16 v[116:119], v[148:151], v[204:207], v[116:119]
	v_mfma_f32_16x16x32_bf16 v[112:115], v[156:159], v[204:207], v[112:115]
	v_mfma_f32_16x16x32_bf16 v[100:103], v[148:151], v[212:215], v[100:103]
	v_mfma_f32_16x16x32_bf16 v[96:99], v[156:159], v[212:215], v[96:99]
	v_mfma_f32_16x16x32_bf16 v[84:87], v[148:151], v[220:223], v[84:87]
	v_mfma_f32_16x16x32_bf16 v[80:83], v[156:159], v[220:223], v[80:83]
	s_setprio 1
	s_barrier
	s_add_i32 s34, s49, s60
	v_lshl_add_u64 v[180:181], v[180:181], 0, s[46:47]
	s_mov_b32 m0, s34
	ds_read_b128 v[192:195], v188 offset:49152
	ds_read_b128 v[196:199], v188 offset:50176
	ds_read_b128 v[200:203], v188 offset:51200
	ds_read_b128 v[204:207], v188 offset:52224
	ds_read_b128 v[208:211], v188 offset:53248
	ds_read_b128 v[212:215], v188 offset:54272
	ds_read_b128 v[216:219], v188 offset:55296
	ds_read_b128 v[220:223], v188 offset:56320
	global_load_lds_dwordx4 v[180:181], off
	s_add_i32 m0, s34, 0x2000
	s_add_u32 s8, s8, 0x40080
	v_lshl_add_u64 v[180:181], v[224:225], 0, s[46:47]
	s_addc_u32 s9, s9, 0
	s_add_i32 s34, s51, s60
	global_load_lds_dwordx4 v[180:181], off
	v_lshl_add_u64 v[180:181], s[8:9], 0, v[162:163]
	s_mov_b32 m0, s34
	s_nop 0
	global_load_lds_dwordx4 v[180:181], off
	v_lshl_add_u64 v[180:181], s[8:9], 0, v[166:167]
	s_add_i32 m0, s34, 0x2000
	s_nop 0
	global_load_lds_dwordx4 v[180:181], off
	v_lshl_add_u64 v[180:181], v[226:227], 0, s[46:47]
	s_mov_b32 m0, s78
	s_nop 0
	global_load_lds_dwordx4 v[180:181], off
	v_lshl_add_u64 v[180:181], v[228:229], 0, s[46:47]
	s_mov_b32 m0, s79
	s_nop 0
	global_load_lds_dwordx4 v[180:181], off
	s_waitcnt vmcnt(8)
	s_waitcnt lgkmcnt(0)
	s_barrier
	s_setprio 0
	s_waitcnt lgkmcnt(0)
	v_mfma_f32_16x16x32_bf16 v[76:79], v[48:51], v[192:195], v[76:79]
	v_mfma_f32_16x16x32_bf16 v[72:75], v[64:67], v[192:195], v[72:75]
	v_mfma_f32_16x16x32_bf16 v[60:63], v[48:51], v[200:203], v[60:63]
	v_mfma_f32_16x16x32_bf16 v[56:59], v[64:67], v[200:203], v[56:59]
	v_mfma_f32_16x16x32_bf16 v[28:31], v[48:51], v[208:211], v[28:31]
	v_mfma_f32_16x16x32_bf16 v[24:27], v[64:67], v[208:211], v[24:27]
	v_mfma_f32_16x16x32_bf16 v[12:15], v[48:51], v[216:219], v[12:15]
	v_mfma_f32_16x16x32_bf16 v[8:11], v[64:67], v[216:219], v[8:11]
	v_mfma_f32_16x16x32_bf16 v[76:79], v[52:55], v[196:199], v[76:79]
	s_add_i32 s33, s33, 2
	v_mfma_f32_16x16x32_bf16 v[72:75], v[68:71], v[196:199], v[72:75]
	s_add_u32 s6, s6, 0x100
	v_mfma_f32_16x16x32_bf16 v[60:63], v[52:55], v[204:207], v[60:63]
	s_addc_u32 s7, s7, 0
	v_mfma_f32_16x16x32_bf16 v[56:59], v[68:71], v[204:207], v[56:59]
	s_add_u32 s25, s25, 0x100
	v_mfma_f32_16x16x32_bf16 v[28:31], v[52:55], v[212:215], v[28:31]
	s_addc_u32 s30, s30, 0
	v_mfma_f32_16x16x32_bf16 v[24:27], v[68:71], v[212:215], v[24:27]
	v_mfma_f32_16x16x32_bf16 v[12:15], v[52:55], v[220:223], v[12:15]
	v_mfma_f32_16x16x32_bf16 v[8:11], v[68:71], v[220:223], v[8:11]
	s_setprio 1
	s_setprio 0
	v_mfma_f32_16x16x32_bf16 v[32:35], v[144:147], v[192:195], v[32:35]
	v_mfma_f32_16x16x32_bf16 v[68:71], v[148:151], v[196:199], v[32:35]
	v_mfma_f32_16x16x32_bf16 v[32:35], v[152:155], v[192:195], v[36:39]
	v_mfma_f32_16x16x32_bf16 v[64:67], v[156:159], v[196:199], v[32:35]
	v_mfma_f32_16x16x32_bf16 v[32:35], v[144:147], v[200:203], v[40:43]
	v_mfma_f32_16x16x32_bf16 v[52:55], v[148:151], v[204:207], v[32:35]
	v_mfma_f32_16x16x32_bf16 v[32:35], v[152:155], v[200:203], v[44:47]
	v_mfma_f32_16x16x32_bf16 v[20:23], v[144:147], v[208:211], v[20:23]
	v_mfma_f32_16x16x32_bf16 v[16:19], v[152:155], v[208:211], v[16:19]
	v_mfma_f32_16x16x32_bf16 v[4:7], v[144:147], v[216:219], v[4:7]
	v_mfma_f32_16x16x32_bf16 v[0:3], v[152:155], v[216:219], v[0:3]
	v_mfma_f32_16x16x32_bf16 v[48:51], v[156:159], v[204:207], v[32:35]
	v_mfma_f32_16x16x32_bf16 v[20:23], v[148:151], v[212:215], v[20:23]
	v_mfma_f32_16x16x32_bf16 v[16:19], v[156:159], v[212:215], v[16:19]
	v_mfma_f32_16x16x32_bf16 v[4:7], v[148:151], v[220:223], v[4:7]
	v_mfma_f32_16x16x32_bf16 v[0:3], v[156:159], v[220:223], v[0:3]
	s_setprio 1
	s_barrier
	s_cmp_gt_u32 s33, 13
	s_cbranch_scc0 .LBB5_625
	s_setprio 0
	s_nop 0
	s_nop 0
	s_nop 0
	s_nop 0
	s_nop 0
	s_nop 0
	s_nop 0
	s_nop 0
	s_nop 0
	s_nop 0
	s_nop 0
	s_nop 0
	s_nop 0
	s_and_b64 vcc, exec, s[42:43]
	s_cbranch_vccz .LBB5_628
	s_barrier

.Lskw_P8:
	s_waitcnt lgkmcnt(0)
	s_barrier
	s_setprio 0
	s_waitcnt lgkmcnt(0)
	v_mfma_f32_16x16x32_bf16 v[124:127], v[128:131], v[176:179], v[124:127]
	v_mfma_f32_16x16x32_bf16 v[120:123], v[136:139], v[176:179], v[120:123]
	v_mfma_f32_16x16x32_bf16 v[108:111], v[128:131], v[194:197], v[108:111]
	v_mfma_f32_16x16x32_bf16 v[104:107], v[136:139], v[194:197], v[104:107]
	v_mfma_f32_16x16x32_bf16 v[92:95], v[128:131], v[202:205], v[92:95]
	v_mfma_f32_16x16x32_bf16 v[88:91], v[136:139], v[202:205], v[88:91]
	v_mfma_f32_16x16x32_bf16 v[76:79], v[128:131], v[210:213], v[76:79]
	v_mfma_f32_16x16x32_bf16 v[72:75], v[136:139], v[210:213], v[72:75]
	v_mfma_f32_16x16x32_bf16 v[124:127], v[132:135], v[180:183], v[124:127]
	v_mfma_f32_16x16x32_bf16 v[120:123], v[140:143], v[180:183], v[120:123]
	v_mfma_f32_16x16x32_bf16 v[108:111], v[132:135], v[198:201], v[108:111]
	v_mfma_f32_16x16x32_bf16 v[104:107], v[140:143], v[198:201], v[104:107]
	v_mfma_f32_16x16x32_bf16 v[92:95], v[132:135], v[206:209], v[92:95]
	v_mfma_f32_16x16x32_bf16 v[88:91], v[140:143], v[206:209], v[88:91]
	v_mfma_f32_16x16x32_bf16 v[76:79], v[132:135], v[214:217], v[76:79]
	v_mfma_f32_16x16x32_bf16 v[72:75], v[140:143], v[214:217], v[72:75]
	s_setprio 1
	s_setprio 0
	v_mfma_f32_16x16x32_bf16 v[116:119], v[144:147], v[176:179], v[116:119]
	v_mfma_f32_16x16x32_bf16 v[112:115], v[168:171], v[176:179], v[112:115]
	v_mfma_f32_16x16x32_bf16 v[100:103], v[144:147], v[194:197], v[100:103]
	v_mfma_f32_16x16x32_bf16 v[96:99], v[168:171], v[194:197], v[96:99]
	v_mfma_f32_16x16x32_bf16 v[84:87], v[144:147], v[202:205], v[84:87]
	v_mfma_f32_16x16x32_bf16 v[80:83], v[168:171], v[202:205], v[80:83]
	v_mfma_f32_16x16x32_bf16 v[68:71], v[144:147], v[210:213], v[68:71]
	v_mfma_f32_16x16x32_bf16 v[64:67], v[168:171], v[210:213], v[64:67]
	v_mfma_f32_16x16x32_bf16 v[116:119], v[148:151], v[180:183], v[116:119]
	v_mfma_f32_16x16x32_bf16 v[112:115], v[172:175], v[180:183], v[112:115]
	v_mfma_f32_16x16x32_bf16 v[100:103], v[148:151], v[198:201], v[100:103]
	v_mfma_f32_16x16x32_bf16 v[96:99], v[172:175], v[198:201], v[96:99]
	v_mfma_f32_16x16x32_bf16 v[84:87], v[148:151], v[206:209], v[84:87]
	v_mfma_f32_16x16x32_bf16 v[80:83], v[172:175], v[206:209], v[80:83]
	v_mfma_f32_16x16x32_bf16 v[68:71], v[148:151], v[214:217], v[68:71]
	v_mfma_f32_16x16x32_bf16 v[64:67], v[172:175], v[214:217], v[64:67]
	s_setprio 1
	s_barrier
	s_add_i32 s58, s51, s33
	v_lshl_add_u64 v[184:185], s[40:41], 0, v[154:155]
	s_mov_b32 m0, s58
	ds_read_b128 v[176:179], v193 offset:16384
	ds_read_b128 v[180:183], v193 offset:17408
	ds_read_b128 v[194:197], v193 offset:18432
	ds_read_b128 v[198:201], v193 offset:19456
	ds_read_b128 v[202:205], v193 offset:20480
	ds_read_b128 v[206:209], v193 offset:21504
	ds_read_b128 v[210:213], v193 offset:22528
	ds_read_b128 v[214:217], v193 offset:23552
	global_load_lds_dwordx4 v[184:185], off
	s_add_i32 m0, s58, 0x2000
	s_add_u32 s58, s40, 0x40000
	v_lshl_add_u64 v[218:219], s[40:41], 0, v[158:159]
	s_addc_u32 s59, s41, 0
	s_add_i32 s60, s52, s33
	global_load_lds_dwordx4 v[218:219], off
	v_lshl_add_u64 v[220:221], s[58:59], 0, v[154:155]
	s_mov_b32 m0, s60
	v_lshl_add_u64 v[222:223], s[42:43], 0, v[156:157]
	global_load_lds_dwordx4 v[220:221], off
	v_lshl_add_u64 v[220:221], s[58:59], 0, v[158:159]
	s_add_i32 m0, s60, 0x2000
	s_nop 0
	global_load_lds_dwordx4 v[220:221], off
	v_lshl_add_u64 v[220:221], s[42:43], 0, v[152:153]
	s_mov_b32 m0, s34
	s_nop 0
	global_load_lds_dwordx4 v[220:221], off
	s_mov_b32 m0, s35
	s_nop 0
	global_load_lds_dwordx4 v[222:223], off
	s_waitcnt vmcnt(8)
	s_waitcnt lgkmcnt(0)
	s_barrier
	s_setprio 0
	s_waitcnt lgkmcnt(0)
	v_mfma_f32_16x16x32_bf16 v[60:63], v[128:131], v[176:179], v[60:63]
	v_mfma_f32_16x16x32_bf16 v[56:59], v[136:139], v[176:179], v[56:59]
	v_mfma_f32_16x16x32_bf16 v[44:47], v[128:131], v[194:197], v[44:47]
	v_mfma_f32_16x16x32_bf16 v[40:43], v[136:139], v[194:197], v[40:43]
	v_mfma_f32_16x16x32_bf16 v[28:31], v[128:131], v[202:205], v[28:31]
	v_mfma_f32_16x16x32_bf16 v[24:27], v[136:139], v[202:205], v[24:27]
	v_mfma_f32_16x16x32_bf16 v[12:15], v[128:131], v[210:213], v[12:15]
	v_mfma_f32_16x16x32_bf16 v[8:11], v[136:139], v[210:213], v[8:11]
	v_mfma_f32_16x16x32_bf16 v[60:63], v[132:135], v[180:183], v[60:63]
	v_mfma_f32_16x16x32_bf16 v[56:59], v[140:143], v[180:183], v[56:59]
	v_mfma_f32_16x16x32_bf16 v[44:47], v[132:135], v[198:201], v[44:47]
	v_mfma_f32_16x16x32_bf16 v[40:43], v[140:143], v[198:201], v[40:43]
	v_mfma_f32_16x16x32_bf16 v[28:31], v[132:135], v[206:209], v[28:31]
	v_mfma_f32_16x16x32_bf16 v[24:27], v[140:143], v[206:209], v[24:27]
	v_mfma_f32_16x16x32_bf16 v[12:15], v[132:135], v[214:217], v[12:15]
	v_mfma_f32_16x16x32_bf16 v[8:11], v[140:143], v[214:217], v[8:11]
	s_setprio 1
	s_setprio 0
	v_mfma_f32_16x16x32_bf16 v[52:55], v[144:147], v[176:179], v[52:55]
	v_mfma_f32_16x16x32_bf16 v[48:51], v[168:171], v[176:179], v[48:51]
	v_mfma_f32_16x16x32_bf16 v[36:39], v[144:147], v[194:197], v[36:39]
	v_mfma_f32_16x16x32_bf16 v[32:35], v[168:171], v[194:197], v[32:35]
	v_mfma_f32_16x16x32_bf16 v[20:23], v[144:147], v[202:205], v[20:23]
	v_mfma_f32_16x16x32_bf16 v[16:19], v[168:171], v[202:205], v[16:19]
	v_mfma_f32_16x16x32_bf16 v[4:7], v[144:147], v[210:213], v[4:7]
	v_mfma_f32_16x16x32_bf16 v[0:3], v[168:171], v[210:213], v[0:3]
	v_mfma_f32_16x16x32_bf16 v[52:55], v[148:151], v[180:183], v[52:55]
	v_mfma_f32_16x16x32_bf16 v[48:51], v[172:175], v[180:183], v[48:51]
	v_mfma_f32_16x16x32_bf16 v[36:39], v[148:151], v[198:201], v[36:39]
	v_mfma_f32_16x16x32_bf16 v[32:35], v[172:175], v[198:201], v[32:35]
	v_mfma_f32_16x16x32_bf16 v[20:23], v[148:151], v[206:209], v[20:23]
	v_mfma_f32_16x16x32_bf16 v[16:19], v[172:175], v[206:209], v[16:19]
	v_mfma_f32_16x16x32_bf16 v[4:7], v[148:151], v[214:217], v[4:7]
	v_mfma_f32_16x16x32_bf16 v[0:3], v[172:175], v[214:217], v[0:3]
	s_setprio 1
	s_barrier
	s_add_i32 s58, 0, 0x18000
	s_add_i32 s59, 0, 0x1c000
	v_add_u32_e32 v140, s58, v187
	v_add_u32_e32 v172, s59, v187
	ds_read_b128 v[128:131], v140
	ds_read_b128 v[132:135], v140 offset:1024
	ds_read_b128 v[136:139], v140 offset:2048
	ds_read_b128 v[140:143], v140 offset:3072
	ds_read_b128 v[144:147], v172
	ds_read_b128 v[148:151], v172 offset:1024
	ds_read_b128 v[168:171], v172 offset:2048
	ds_read_b128 v[172:175], v172 offset:3072
	s_add_u32 s42, s42, 0x40000
	s_addc_u32 s43, s43, 0
	s_mov_b32 m0, s44
	v_lshl_add_u64 v[224:225], s[42:43], 0, v[152:153]
	ds_read_b128 v[176:179], v193 offset:32768
	ds_read_b128 v[180:183], v193 offset:33792
	ds_read_b128 v[194:197], v193 offset:34816
	ds_read_b128 v[198:201], v193 offset:35840
	ds_read_b128 v[202:205], v193 offset:36864
	ds_read_b128 v[206:209], v193 offset:37888
	ds_read_b128 v[210:213], v193 offset:38912
	ds_read_b128 v[214:217], v193 offset:39936
	global_load_lds_dwordx4 v[224:225], off
	v_lshl_add_u64 v[224:225], s[42:43], 0, v[156:157]
	s_mov_b32 m0, s45
	s_nop 0
	global_load_lds_dwordx4 v[224:225], off
	s_waitcnt vmcnt(8)
	s_waitcnt lgkmcnt(0)
	s_barrier
	s_setprio 0
	s_waitcnt lgkmcnt(0)
	v_mfma_f32_16x16x32_bf16 v[124:127], v[128:131], v[176:179], v[124:127]
	v_mfma_f32_16x16x32_bf16 v[120:123], v[136:139], v[176:179], v[120:123]
	v_mfma_f32_16x16x32_bf16 v[108:111], v[128:131], v[194:197], v[108:111]
	v_mfma_f32_16x16x32_bf16 v[104:107], v[136:139], v[194:197], v[104:107]
	v_mfma_f32_16x16x32_bf16 v[92:95], v[128:131], v[202:205], v[92:95]
	v_mfma_f32_16x16x32_bf16 v[88:91], v[136:139], v[202:205], v[88:91]
	v_mfma_f32_16x16x32_bf16 v[76:79], v[128:131], v[210:213], v[76:79]
	v_mfma_f32_16x16x32_bf16 v[72:75], v[136:139], v[210:213], v[72:75]
	v_mfma_f32_16x16x32_bf16 v[124:127], v[132:135], v[180:183], v[124:127]
	v_mfma_f32_16x16x32_bf16 v[120:123], v[140:143], v[180:183], v[120:123]
	v_mfma_f32_16x16x32_bf16 v[108:111], v[132:135], v[198:201], v[108:111]
	v_mfma_f32_16x16x32_bf16 v[104:107], v[140:143], v[198:201], v[104:107]
	v_mfma_f32_16x16x32_bf16 v[92:95], v[132:135], v[206:209], v[92:95]
	v_mfma_f32_16x16x32_bf16 v[88:91], v[140:143], v[206:209], v[88:91]
	v_mfma_f32_16x16x32_bf16 v[76:79], v[132:135], v[214:217], v[76:79]
	v_mfma_f32_16x16x32_bf16 v[72:75], v[140:143], v[214:217], v[72:75]
	s_setprio 1
	s_setprio 0
	v_mfma_f32_16x16x32_bf16 v[116:119], v[144:147], v[176:179], v[116:119]
	v_mfma_f32_16x16x32_bf16 v[112:115], v[168:171], v[176:179], v[112:115]
	v_mfma_f32_16x16x32_bf16 v[100:103], v[144:147], v[194:197], v[100:103]
	v_mfma_f32_16x16x32_bf16 v[96:99], v[168:171], v[194:197], v[96:99]
	v_mfma_f32_16x16x32_bf16 v[84:87], v[144:147], v[202:205], v[84:87]
	v_mfma_f32_16x16x32_bf16 v[80:83], v[168:171], v[202:205], v[80:83]
	v_mfma_f32_16x16x32_bf16 v[68:71], v[144:147], v[210:213], v[68:71]
	v_mfma_f32_16x16x32_bf16 v[64:67], v[168:171], v[210:213], v[64:67]
	v_mfma_f32_16x16x32_bf16 v[116:119], v[148:151], v[180:183], v[116:119]
	v_mfma_f32_16x16x32_bf16 v[112:115], v[172:175], v[180:183], v[112:115]
	v_mfma_f32_16x16x32_bf16 v[100:103], v[148:151], v[198:201], v[100:103]
	v_mfma_f32_16x16x32_bf16 v[96:99], v[172:175], v[198:201], v[96:99]
	v_mfma_f32_16x16x32_bf16 v[84:87], v[148:151], v[206:209], v[84:87]
	v_mfma_f32_16x16x32_bf16 v[80:83], v[172:175], v[206:209], v[80:83]
	v_mfma_f32_16x16x32_bf16 v[68:71], v[148:151], v[214:217], v[68:71]
	v_mfma_f32_16x16x32_bf16 v[64:67], v[172:175], v[214:217], v[64:67]
	s_setprio 1
	s_barrier
	s_add_i32 s42, s58, s33
	v_lshl_add_u64 v[184:185], v[184:185], 0, s[18:19]
	s_mov_b32 m0, s42
	ds_read_b128 v[176:179], v193 offset:49152
	ds_read_b128 v[180:183], v193 offset:50176
	ds_read_b128 v[194:197], v193 offset:51200
	ds_read_b128 v[198:201], v193 offset:52224
	ds_read_b128 v[202:205], v193 offset:53248
	ds_read_b128 v[206:209], v193 offset:54272
	ds_read_b128 v[210:213], v193 offset:55296
	ds_read_b128 v[214:217], v193 offset:56320
	global_load_lds_dwordx4 v[184:185], off
	s_add_i32 m0, s42, 0x2000
	s_add_u32 s40, s40, 0x40080
	v_lshl_add_u64 v[184:185], v[218:219], 0, s[18:19]
	s_addc_u32 s41, s41, 0
	s_add_i32 s42, s59, s33
	global_load_lds_dwordx4 v[184:185], off
	v_lshl_add_u64 v[184:185], s[40:41], 0, v[154:155]
	s_mov_b32 m0, s42
	s_nop 0
	global_load_lds_dwordx4 v[184:185], off
	v_lshl_add_u64 v[184:185], s[40:41], 0, v[158:159]
	s_add_i32 m0, s42, 0x2000
	s_nop 0
	global_load_lds_dwordx4 v[184:185], off
	v_lshl_add_u64 v[184:185], v[220:221], 0, s[18:19]
	s_mov_b32 m0, s49
	s_nop 0
	global_load_lds_dwordx4 v[184:185], off
	v_lshl_add_u64 v[184:185], v[222:223], 0, s[18:19]
	s_mov_b32 m0, s50
	s_nop 0
	global_load_lds_dwordx4 v[184:185], off
	s_waitcnt vmcnt(8)
	s_waitcnt lgkmcnt(0)
	s_barrier
	s_setprio 0
	s_waitcnt lgkmcnt(0)
	v_mfma_f32_16x16x32_bf16 v[60:63], v[128:131], v[176:179], v[60:63]
	v_mfma_f32_16x16x32_bf16 v[56:59], v[136:139], v[176:179], v[56:59]
	v_mfma_f32_16x16x32_bf16 v[44:47], v[128:131], v[194:197], v[44:47]
	v_mfma_f32_16x16x32_bf16 v[40:43], v[136:139], v[194:197], v[40:43]
	v_mfma_f32_16x16x32_bf16 v[28:31], v[128:131], v[202:205], v[28:31]
	v_mfma_f32_16x16x32_bf16 v[24:27], v[136:139], v[202:205], v[24:27]
	v_mfma_f32_16x16x32_bf16 v[12:15], v[128:131], v[210:213], v[12:15]
	v_mfma_f32_16x16x32_bf16 v[8:11], v[136:139], v[210:213], v[8:11]
	v_mfma_f32_16x16x32_bf16 v[60:63], v[132:135], v[180:183], v[60:63]
	s_add_i32 s57, s57, 2
	v_mfma_f32_16x16x32_bf16 v[56:59], v[140:143], v[180:183], v[56:59]
	s_add_u32 s38, s38, 0x100
	v_mfma_f32_16x16x32_bf16 v[44:47], v[132:135], v[198:201], v[44:47]
	s_addc_u32 s39, s39, 0
	v_mfma_f32_16x16x32_bf16 v[40:43], v[140:143], v[198:201], v[40:43]
	s_add_u32 s55, s55, 0x100
	v_mfma_f32_16x16x32_bf16 v[28:31], v[132:135], v[206:209], v[28:31]
	s_addc_u32 s56, s56, 0
	v_mfma_f32_16x16x32_bf16 v[24:27], v[140:143], v[206:209], v[24:27]
	v_mfma_f32_16x16x32_bf16 v[12:15], v[132:135], v[214:217], v[12:15]
	v_mfma_f32_16x16x32_bf16 v[8:11], v[140:143], v[214:217], v[8:11]
	s_setprio 1
	s_setprio 0
	v_mfma_f32_16x16x32_bf16 v[52:55], v[144:147], v[176:179], v[52:55]
	v_mfma_f32_16x16x32_bf16 v[48:51], v[168:171], v[176:179], v[48:51]
	v_mfma_f32_16x16x32_bf16 v[36:39], v[144:147], v[194:197], v[36:39]
	v_mfma_f32_16x16x32_bf16 v[32:35], v[168:171], v[194:197], v[32:35]
	v_mfma_f32_16x16x32_bf16 v[20:23], v[144:147], v[202:205], v[20:23]
	v_mfma_f32_16x16x32_bf16 v[16:19], v[168:171], v[202:205], v[16:19]
	v_mfma_f32_16x16x32_bf16 v[4:7], v[144:147], v[210:213], v[4:7]
	v_mfma_f32_16x16x32_bf16 v[0:3], v[168:171], v[210:213], v[0:3]
	v_mfma_f32_16x16x32_bf16 v[52:55], v[148:151], v[180:183], v[52:55]
	v_mfma_f32_16x16x32_bf16 v[48:51], v[172:175], v[180:183], v[48:51]
	v_mfma_f32_16x16x32_bf16 v[36:39], v[148:151], v[198:201], v[36:39]
	v_mfma_f32_16x16x32_bf16 v[32:35], v[172:175], v[198:201], v[32:35]
	v_mfma_f32_16x16x32_bf16 v[20:23], v[148:151], v[206:209], v[20:23]
	v_mfma_f32_16x16x32_bf16 v[16:19], v[172:175], v[206:209], v[16:19]
	v_mfma_f32_16x16x32_bf16 v[4:7], v[148:151], v[214:217], v[4:7]
	v_mfma_f32_16x16x32_bf16 v[0:3], v[172:175], v[214:217], v[0:3]
	s_setprio 1
	s_barrier
	s_cmp_gt_u32 s57, 13
	s_cbranch_scc0 .LBB5_969
	s_setprio 0
	s_nop 0
	s_nop 0
	s_nop 0
	s_nop 0
	s_nop 0
	s_nop 0
	s_nop 0
	s_nop 0
	s_nop 0
	s_nop 0
	s_nop 0
	s_nop 0
	s_nop 0
	s_and_b64 vcc, exec, s[16:17]
	s_cbranch_vccz .LBB5_972
	s_barrier
